# K-loop: DMAs spread over the whole period, s_setprio 3, snake MFMA order (B-stationary pairs)
# speedup vs baseline: 1.1008x; 1.0125x over previous
.LBB0_157:
	s_andn2_b64 vcc, exec, s[20:21]
	s_cbranch_vccnz .LBB0_154
	s_lshl_b32 s21, s46, 7
	v_lshlrev_b32_e32 v0, 3, v108
	s_and_b32 s49, s21, 0x380
	v_ashrrev_i32_e32 v36, 3, v108
	v_and_b32_e32 v37, 56, v0
	v_add_u32_e32 v0, s49, v36
	s_movk_i32 s24, 0xb00
	s_lshl_b32 s20, s46, 4
	v_mul_lo_u32 v0, v0, s24
	s_and_b32 s47, s20, 0xffffff80
	v_or_b32_e32 v0, v0, v37
	s_waitcnt lgkmcnt(0)
	v_lshl_add_u64 v[2:3], v[0:1], 1, s[26:27]
	v_add_u32_e32 v0, s47, v36
	v_mul_lo_u32 v0, v0, s24
	v_or_b32_e32 v0, v0, v37
	v_lshl_add_u64 v[12:13], v[0:1], 1, s[90:91]
	v_mov_b32_e32 v74, v12
	v_mov_b32_e32 v75, v13
	v_mov_b32_e32 v72, v2
	v_mov_b32_e32 v73, v3
	v_mov_b32_e32 v104, 0x2c000
	v_mov_b32_e32 v105, 0
	v_lshl_add_u64 v[76:77], v[74:75], 0, v[104:105]
	v_lshl_add_u64 v[78:79], v[76:77], 0, v[104:105]
	v_lshl_add_u64 v[80:81], v[78:79], 0, v[104:105]
	v_lshl_add_u64 v[82:83], v[72:73], 0, v[104:105]
	v_lshl_add_u64 v[84:85], v[82:83], 0, v[104:105]
	v_lshl_add_u64 v[86:87], v[84:85], 0, v[104:105]
	v_and_b32_e32 v110, 31, v108
	v_ashrrev_i32_e32 v0, 1, v108
	v_and_b32_e32 v111, 0xffffffc0, v0
	v_readlane_b32 s52, v252, 4
	v_readlane_b32 s66, v252, 18
	v_readlane_b32 s67, v252, 19
	v_readlane_b32 s53, v252, 5
	v_readlane_b32 s54, v252, 6
	v_readlane_b32 s55, v252, 7
	v_readlane_b32 s56, v252, 8
	v_readlane_b32 s57, v252, 9
	v_readlane_b32 s58, v252, 10
	v_readlane_b32 s59, v252, 11
	v_readlane_b32 s60, v252, 12
	v_readlane_b32 s61, v252, 13
	v_readlane_b32 s62, v252, 14
	v_readlane_b32 s63, v252, 15
	v_readlane_b32 s64, v252, 16
	v_readlane_b32 s65, v252, 17
	s_barrier
	v_bfe_u32 v102, v108, 4, 3
	v_lshlrev_b32_e32 v102, 4, v102
	v_xor_b32_e32 v74, v102, v74
	v_xor_b32_e32 v76, v102, v76
	v_xor_b32_e32 v78, v102, v78
	v_xor_b32_e32 v80, v102, v80
	v_xor_b32_e32 v72, v102, v72
	v_xor_b32_e32 v82, v102, v82
	v_xor_b32_e32 v84, v102, v84
	v_xor_b32_e32 v86, v102, v86
	v_bfe_u32 v102, v108, 5, 1
	v_bfe_u32 v103, v108, 1, 3
	v_xor_b32_e32 v102, v102, v103
	v_lshlrev_b32_e32 v102, 4, v102
	v_lshrrev_b32_e32 v103, 1, v108
	v_and_b32_e32 v103, 64, v103
	v_and_b32_e32 v104, 31, v108
	v_or_b32_e32 v103, v103, v104
	v_lshl_or_b32 v94, v103, 7, v102
	v_and_b32_e32 v103, 0x5f, v108
	v_lshl_or_b32 v98, v103, 7, v102
	v_add_u32_e32 v98, 0x4000, v98
	v_xor_b32_e32 v95, 0x20, v94
	v_xor_b32_e32 v99, 0x20, v98
	v_xor_b32_e32 v96, 0x40, v94
	v_xor_b32_e32 v100, 0x40, v98
	v_xor_b32_e32 v97, 0x60, v94
	v_xor_b32_e32 v101, 0x60, v98
	v_mov_b32_e32 v214, 0x80
	v_mov_b32_e32 v215, 0
	s_lshl_b32 vcc_lo, s80, 4
	v_mov_b32_e32 v2, 0
	v_mov_b32_e32 v3, 0
	v_mov_b32_e32 v4, 0
	v_mov_b32_e32 v5, 0
	v_mov_b32_e32 v6, 0
	v_mov_b32_e32 v7, 0
	v_mov_b32_e32 v8, 0
	v_mov_b32_e32 v9, 0
	v_mov_b32_e32 v10, 0
	v_mov_b32_e32 v11, 0
	v_mov_b32_e32 v12, 0
	v_mov_b32_e32 v13, 0
	v_mov_b32_e32 v14, 0
	v_mov_b32_e32 v15, 0
	v_mov_b32_e32 v16, 0
	v_mov_b32_e32 v17, 0
	v_mov_b32_e32 v18, 0
	v_mov_b32_e32 v19, 0
	v_mov_b32_e32 v20, 0
	v_mov_b32_e32 v21, 0
	v_mov_b32_e32 v22, 0
	v_mov_b32_e32 v23, 0
	v_mov_b32_e32 v24, 0
	v_mov_b32_e32 v25, 0
	v_mov_b32_e32 v26, 0
	v_mov_b32_e32 v27, 0
	v_mov_b32_e32 v28, 0
	v_mov_b32_e32 v29, 0
	v_mov_b32_e32 v30, 0
	v_mov_b32_e32 v31, 0
	v_mov_b32_e32 v32, 0
	v_mov_b32_e32 v33, 0
	v_mov_b32_e32 v34, 0
	v_mov_b32_e32 v35, 0
	v_mov_b32_e32 v36, 0
	v_mov_b32_e32 v37, 0
	v_mov_b32_e32 v38, 0
	v_mov_b32_e32 v39, 0
	v_mov_b32_e32 v40, 0
	v_mov_b32_e32 v41, 0
	v_mov_b32_e32 v42, 0
	v_mov_b32_e32 v43, 0
	v_mov_b32_e32 v44, 0
	v_mov_b32_e32 v45, 0
	v_mov_b32_e32 v46, 0
	v_mov_b32_e32 v47, 0
	v_mov_b32_e32 v48, 0
	v_mov_b32_e32 v49, 0
	v_mov_b32_e32 v50, 0
	v_mov_b32_e32 v51, 0
	v_mov_b32_e32 v52, 0
	v_mov_b32_e32 v53, 0
	v_mov_b32_e32 v54, 0
	v_mov_b32_e32 v55, 0
	v_mov_b32_e32 v56, 0
	v_mov_b32_e32 v57, 0
	v_mov_b32_e32 v58, 0
	v_mov_b32_e32 v59, 0
	v_mov_b32_e32 v60, 0
	v_mov_b32_e32 v61, 0
	v_mov_b32_e32 v62, 0
	v_mov_b32_e32 v63, 0
	v_mov_b32_e32 v64, 0
	v_mov_b32_e32 v65, 0
	s_mov_b32 m0, vcc_lo
	s_nop 0
	global_load_lds_dwordx4 v[74:75], off
	s_add_u32 m0, vcc_lo, 0x1000
	s_nop 0
	global_load_lds_dwordx4 v[76:77], off
	s_add_u32 m0, vcc_lo, 0x2000
	s_nop 0
	global_load_lds_dwordx4 v[78:79], off
	s_add_u32 m0, vcc_lo, 0x3000
	s_nop 0
	global_load_lds_dwordx4 v[80:81], off
	s_add_u32 m0, vcc_lo, 0x4000
	s_nop 0
	global_load_lds_dwordx4 v[72:73], off
	s_add_u32 m0, vcc_lo, 0x5000
	s_nop 0
	global_load_lds_dwordx4 v[82:83], off
	s_add_u32 m0, vcc_lo, 0x6000
	s_nop 0
	global_load_lds_dwordx4 v[84:85], off
	s_add_u32 m0, vcc_lo, 0x7000
	s_nop 0
	global_load_lds_dwordx4 v[86:87], off
	v_lshl_add_u64 v[74:75], v[74:75], 0, v[214:215]
	v_lshl_add_u64 v[76:77], v[76:77], 0, v[214:215]
	v_lshl_add_u64 v[78:79], v[78:79], 0, v[214:215]
	v_lshl_add_u64 v[80:81], v[80:81], 0, v[214:215]
	v_lshl_add_u64 v[72:73], v[72:73], 0, v[214:215]
	v_lshl_add_u64 v[82:83], v[82:83], 0, v[214:215]
	v_lshl_add_u64 v[84:85], v[84:85], 0, v[214:215]
	v_lshl_add_u64 v[86:87], v[86:87], 0, v[214:215]
	s_add_u32 m0, vcc_lo, 0x8000
	s_nop 0
	global_load_lds_dwordx4 v[74:75], off
	s_add_u32 m0, vcc_lo, 0x9000
	s_nop 0
	global_load_lds_dwordx4 v[76:77], off
	s_add_u32 m0, vcc_lo, 0xa000
	s_nop 0
	global_load_lds_dwordx4 v[78:79], off
	s_add_u32 m0, vcc_lo, 0xb000
	s_nop 0
	global_load_lds_dwordx4 v[80:81], off
	s_add_u32 m0, vcc_lo, 0xc000
	s_nop 0
	global_load_lds_dwordx4 v[72:73], off
	s_add_u32 m0, vcc_lo, 0xd000
	s_nop 0
	global_load_lds_dwordx4 v[82:83], off
	s_add_u32 m0, vcc_lo, 0xe000
	s_nop 0
	global_load_lds_dwordx4 v[84:85], off
	s_add_u32 m0, vcc_lo, 0xf000
	s_nop 0
	global_load_lds_dwordx4 v[86:87], off
	v_lshl_add_u64 v[74:75], v[74:75], 0, v[214:215]
	v_lshl_add_u64 v[76:77], v[76:77], 0, v[214:215]
	v_lshl_add_u64 v[78:79], v[78:79], 0, v[214:215]
	v_lshl_add_u64 v[80:81], v[80:81], 0, v[214:215]
	v_lshl_add_u64 v[72:73], v[72:73], 0, v[214:215]
	v_lshl_add_u64 v[82:83], v[82:83], 0, v[214:215]
	v_lshl_add_u64 v[84:85], v[84:85], 0, v[214:215]
	v_lshl_add_u64 v[86:87], v[86:87], 0, v[214:215]
	s_mov_b32 vcc_hi, 21
	s_waitcnt vmcnt(8)
	s_barrier
	ds_read_b128 v[166:169], v94
	s_setprio 3
	ds_read_b128 v[170:173], v98
	ds_read_b128 v[174:177], v98 offset:4096
	ds_read_b128 v[178:181], v94 offset:4096
	ds_read_b128 v[182:185], v95
	ds_read_b128 v[188:191], v99
	ds_read_b128 v[192:195], v99 offset:4096
	ds_read_b128 v[206:209], v95 offset:4096
	s_waitcnt lgkmcnt(6)
	v_mfma_f32_32x32x16_bf16 v[50:65], v[166:169], v[170:173], v[50:65]
	ds_read_b128 v[236:239], v96
	s_waitcnt lgkmcnt(5)
	v_mfma_f32_32x32x16_bf16 v[18:33], v[178:181], v[170:173], v[18:33]
	ds_read_b128 v[240:243], v100
	v_mfma_f32_32x32x16_bf16 v[2:17], v[178:181], v[174:177], v[2:17]
	ds_read_b128 v[244:247], v100 offset:4096
	v_mfma_f32_32x32x16_bf16 v[34:49], v[166:169], v[174:177], v[34:49]
	ds_read_b128 v[248:251], v96 offset:4096
	s_waitcnt lgkmcnt(6)
	v_mfma_f32_32x32x16_bf16 v[50:65], v[182:185], v[188:191], v[50:65]
	ds_read_b128 v[126:129], v97
	s_waitcnt lgkmcnt(5)
	v_mfma_f32_32x32x16_bf16 v[18:33], v[206:209], v[188:191], v[18:33]
	ds_read_b128 v[130:133], v101
	v_mfma_f32_32x32x16_bf16 v[2:17], v[206:209], v[192:195], v[2:17]
	ds_read_b128 v[210:213], v101 offset:4096
	v_mfma_f32_32x32x16_bf16 v[34:49], v[182:185], v[192:195], v[34:49]
	ds_read_b128 v[222:225], v97 offset:4096
	s_waitcnt vmcnt(0) lgkmcnt(0)
	s_barrier
.Lg_resid1_loop:
	v_mfma_f32_32x32x16_bf16 v[50:65], v[236:239], v[240:243], v[50:65]
	s_mov_b32 m0, vcc_lo
	ds_read_b128 v[166:169], v94 offset:32768
	global_load_lds_dwordx4 v[74:75], off
	s_setprio 3
	v_mfma_f32_32x32x16_bf16 v[18:33], v[248:251], v[240:243], v[18:33]
	ds_read_b128 v[170:173], v98 offset:32768
	v_mfma_f32_32x32x16_bf16 v[2:17], v[248:251], v[244:247], v[2:17]
	s_add_u32 m0, vcc_lo, 0x1000
	ds_read_b128 v[174:177], v98 offset:36864
	global_load_lds_dwordx4 v[76:77], off
	v_mfma_f32_32x32x16_bf16 v[34:49], v[236:239], v[244:247], v[34:49]
	ds_read_b128 v[178:181], v94 offset:36864
	v_mfma_f32_32x32x16_bf16 v[50:65], v[126:129], v[130:133], v[50:65]
	s_add_u32 m0, vcc_lo, 0x2000
	ds_read_b128 v[182:185], v95 offset:32768
	global_load_lds_dwordx4 v[78:79], off
	v_mfma_f32_32x32x16_bf16 v[18:33], v[222:225], v[130:133], v[18:33]
	ds_read_b128 v[188:191], v99 offset:32768
	v_mfma_f32_32x32x16_bf16 v[2:17], v[222:225], v[210:213], v[2:17]
	s_add_u32 m0, vcc_lo, 0x3000
	ds_read_b128 v[192:195], v99 offset:36864
	global_load_lds_dwordx4 v[80:81], off
	v_mfma_f32_32x32x16_bf16 v[34:49], v[126:129], v[210:213], v[34:49]
	ds_read_b128 v[206:209], v95 offset:36864
	s_waitcnt lgkmcnt(6)
	v_mfma_f32_32x32x16_bf16 v[50:65], v[166:169], v[170:173], v[50:65]
	s_add_u32 m0, vcc_lo, 0x4000
	ds_read_b128 v[236:239], v96 offset:32768
	global_load_lds_dwordx4 v[72:73], off
	s_waitcnt lgkmcnt(5)
	v_mfma_f32_32x32x16_bf16 v[18:33], v[178:181], v[170:173], v[18:33]
	ds_read_b128 v[240:243], v100 offset:32768
	v_mfma_f32_32x32x16_bf16 v[2:17], v[178:181], v[174:177], v[2:17]
	s_add_u32 m0, vcc_lo, 0x5000
	ds_read_b128 v[244:247], v100 offset:36864
	global_load_lds_dwordx4 v[82:83], off
	v_mfma_f32_32x32x16_bf16 v[34:49], v[166:169], v[174:177], v[34:49]
	ds_read_b128 v[248:251], v96 offset:36864
	s_waitcnt lgkmcnt(6)
	v_mfma_f32_32x32x16_bf16 v[50:65], v[182:185], v[188:191], v[50:65]
	s_add_u32 m0, vcc_lo, 0x6000
	ds_read_b128 v[126:129], v97 offset:32768
	global_load_lds_dwordx4 v[84:85], off
	s_waitcnt lgkmcnt(5)
	v_mfma_f32_32x32x16_bf16 v[18:33], v[206:209], v[188:191], v[18:33]
	ds_read_b128 v[130:133], v101 offset:32768
	v_mfma_f32_32x32x16_bf16 v[2:17], v[206:209], v[192:195], v[2:17]
	s_add_u32 m0, vcc_lo, 0x7000
	ds_read_b128 v[210:213], v101 offset:36864
	global_load_lds_dwordx4 v[86:87], off
	v_mfma_f32_32x32x16_bf16 v[34:49], v[182:185], v[192:195], v[34:49]
	ds_read_b128 v[222:225], v97 offset:36864
	v_lshl_add_u64 v[74:75], v[74:75], 0, v[214:215]
	v_lshl_add_u64 v[76:77], v[76:77], 0, v[214:215]
	v_lshl_add_u64 v[78:79], v[78:79], 0, v[214:215]
	v_lshl_add_u64 v[80:81], v[80:81], 0, v[214:215]
	v_lshl_add_u64 v[72:73], v[72:73], 0, v[214:215]
	v_lshl_add_u64 v[82:83], v[82:83], 0, v[214:215]
	v_lshl_add_u64 v[84:85], v[84:85], 0, v[214:215]
	v_lshl_add_u64 v[86:87], v[86:87], 0, v[214:215]
	s_waitcnt vmcnt(0) lgkmcnt(0)
	s_barrier
	v_mfma_f32_32x32x16_bf16 v[50:65], v[236:239], v[240:243], v[50:65]
	s_add_u32 m0, vcc_lo, 0x8000
	ds_read_b128 v[166:169], v94
	global_load_lds_dwordx4 v[74:75], off
	s_setprio 3
	v_mfma_f32_32x32x16_bf16 v[18:33], v[248:251], v[240:243], v[18:33]
	ds_read_b128 v[170:173], v98
	v_mfma_f32_32x32x16_bf16 v[2:17], v[248:251], v[244:247], v[2:17]
	s_add_u32 m0, vcc_lo, 0x9000
	ds_read_b128 v[174:177], v98 offset:4096
	global_load_lds_dwordx4 v[76:77], off
	v_mfma_f32_32x32x16_bf16 v[34:49], v[236:239], v[244:247], v[34:49]
	ds_read_b128 v[178:181], v94 offset:4096
	v_mfma_f32_32x32x16_bf16 v[50:65], v[126:129], v[130:133], v[50:65]
	s_add_u32 m0, vcc_lo, 0xa000
	ds_read_b128 v[182:185], v95
	global_load_lds_dwordx4 v[78:79], off
	v_mfma_f32_32x32x16_bf16 v[18:33], v[222:225], v[130:133], v[18:33]
	ds_read_b128 v[188:191], v99
	v_mfma_f32_32x32x16_bf16 v[2:17], v[222:225], v[210:213], v[2:17]
	s_add_u32 m0, vcc_lo, 0xb000
	ds_read_b128 v[192:195], v99 offset:4096
	global_load_lds_dwordx4 v[80:81], off
	v_mfma_f32_32x32x16_bf16 v[34:49], v[126:129], v[210:213], v[34:49]
	ds_read_b128 v[206:209], v95 offset:4096
	s_waitcnt lgkmcnt(6)
	v_mfma_f32_32x32x16_bf16 v[50:65], v[166:169], v[170:173], v[50:65]
	s_add_u32 m0, vcc_lo, 0xc000
	ds_read_b128 v[236:239], v96
	global_load_lds_dwordx4 v[72:73], off
	s_waitcnt lgkmcnt(5)
	v_mfma_f32_32x32x16_bf16 v[18:33], v[178:181], v[170:173], v[18:33]
	ds_read_b128 v[240:243], v100
	v_mfma_f32_32x32x16_bf16 v[2:17], v[178:181], v[174:177], v[2:17]
	s_add_u32 m0, vcc_lo, 0xd000
	ds_read_b128 v[244:247], v100 offset:4096
	global_load_lds_dwordx4 v[82:83], off
	v_mfma_f32_32x32x16_bf16 v[34:49], v[166:169], v[174:177], v[34:49]
	ds_read_b128 v[248:251], v96 offset:4096
	s_waitcnt lgkmcnt(6)
	v_mfma_f32_32x32x16_bf16 v[50:65], v[182:185], v[188:191], v[50:65]
	s_add_u32 m0, vcc_lo, 0xe000
	ds_read_b128 v[126:129], v97
	global_load_lds_dwordx4 v[84:85], off
	s_waitcnt lgkmcnt(5)
	v_mfma_f32_32x32x16_bf16 v[18:33], v[206:209], v[188:191], v[18:33]
	ds_read_b128 v[130:133], v101
	v_mfma_f32_32x32x16_bf16 v[2:17], v[206:209], v[192:195], v[2:17]
	s_add_u32 m0, vcc_lo, 0xf000
	ds_read_b128 v[210:213], v101 offset:4096
	global_load_lds_dwordx4 v[86:87], off
	v_mfma_f32_32x32x16_bf16 v[34:49], v[182:185], v[192:195], v[34:49]
	ds_read_b128 v[222:225], v97 offset:4096
	v_lshl_add_u64 v[74:75], v[74:75], 0, v[214:215]
	v_lshl_add_u64 v[76:77], v[76:77], 0, v[214:215]
	v_lshl_add_u64 v[78:79], v[78:79], 0, v[214:215]
	v_lshl_add_u64 v[80:81], v[80:81], 0, v[214:215]
	v_lshl_add_u64 v[72:73], v[72:73], 0, v[214:215]
	v_lshl_add_u64 v[82:83], v[82:83], 0, v[214:215]
	v_lshl_add_u64 v[84:85], v[84:85], 0, v[214:215]
	v_lshl_add_u64 v[86:87], v[86:87], 0, v[214:215]
	s_waitcnt vmcnt(0) lgkmcnt(0)
	s_barrier
	s_sub_u32 vcc_hi, vcc_hi, 1
	s_cmp_lg_u32 vcc_hi, 0
	s_cbranch_scc1 .Lg_resid1_loop
	v_mfma_f32_32x32x16_bf16 v[50:65], v[236:239], v[240:243], v[50:65]
	ds_read_b128 v[166:169], v94 offset:32768
	s_setprio 3
	v_mfma_f32_32x32x16_bf16 v[18:33], v[248:251], v[240:243], v[18:33]
	ds_read_b128 v[170:173], v98 offset:32768
	v_mfma_f32_32x32x16_bf16 v[2:17], v[248:251], v[244:247], v[2:17]
	ds_read_b128 v[174:177], v98 offset:36864
	v_mfma_f32_32x32x16_bf16 v[34:49], v[236:239], v[244:247], v[34:49]
	ds_read_b128 v[178:181], v94 offset:36864
	v_mfma_f32_32x32x16_bf16 v[50:65], v[126:129], v[130:133], v[50:65]
	ds_read_b128 v[182:185], v95 offset:32768
	v_mfma_f32_32x32x16_bf16 v[18:33], v[222:225], v[130:133], v[18:33]
	ds_read_b128 v[188:191], v99 offset:32768
	v_mfma_f32_32x32x16_bf16 v[2:17], v[222:225], v[210:213], v[2:17]
	ds_read_b128 v[192:195], v99 offset:36864
	v_mfma_f32_32x32x16_bf16 v[34:49], v[126:129], v[210:213], v[34:49]
	ds_read_b128 v[206:209], v95 offset:36864
	s_waitcnt lgkmcnt(6)
	v_mfma_f32_32x32x16_bf16 v[50:65], v[166:169], v[170:173], v[50:65]
	ds_read_b128 v[236:239], v96 offset:32768
	s_waitcnt lgkmcnt(5)
	v_mfma_f32_32x32x16_bf16 v[18:33], v[178:181], v[170:173], v[18:33]
	ds_read_b128 v[240:243], v100 offset:32768
	v_mfma_f32_32x32x16_bf16 v[2:17], v[178:181], v[174:177], v[2:17]
	ds_read_b128 v[244:247], v100 offset:36864
	v_mfma_f32_32x32x16_bf16 v[34:49], v[166:169], v[174:177], v[34:49]
	ds_read_b128 v[248:251], v96 offset:36864
	s_waitcnt lgkmcnt(6)
	v_mfma_f32_32x32x16_bf16 v[50:65], v[182:185], v[188:191], v[50:65]
	ds_read_b128 v[126:129], v97 offset:32768
	s_waitcnt lgkmcnt(5)
	v_mfma_f32_32x32x16_bf16 v[18:33], v[206:209], v[188:191], v[18:33]
	ds_read_b128 v[130:133], v101 offset:32768
	v_mfma_f32_32x32x16_bf16 v[2:17], v[206:209], v[192:195], v[2:17]
	ds_read_b128 v[210:213], v101 offset:36864
	v_mfma_f32_32x32x16_bf16 v[34:49], v[182:185], v[192:195], v[34:49]
	ds_read_b128 v[222:225], v97 offset:36864
	s_waitcnt lgkmcnt(6)
	v_mfma_f32_32x32x16_bf16 v[50:65], v[236:239], v[240:243], v[50:65]
	s_waitcnt lgkmcnt(5)
	v_mfma_f32_32x32x16_bf16 v[34:49], v[236:239], v[244:247], v[34:49]
	s_waitcnt lgkmcnt(4)
	v_mfma_f32_32x32x16_bf16 v[18:33], v[248:251], v[240:243], v[18:33]
	v_mfma_f32_32x32x16_bf16 v[2:17], v[248:251], v[244:247], v[2:17]
	s_waitcnt lgkmcnt(2)
	v_mfma_f32_32x32x16_bf16 v[50:65], v[126:129], v[130:133], v[50:65]
	s_waitcnt lgkmcnt(1)
	v_mfma_f32_32x32x16_bf16 v[34:49], v[126:129], v[210:213], v[34:49]
	s_waitcnt lgkmcnt(0)
	v_mfma_f32_32x32x16_bf16 v[18:33], v[222:225], v[130:133], v[18:33]
	v_mfma_f32_32x32x16_bf16 v[2:17], v[222:225], v[210:213], v[2:17]
	s_nop 7
	s_nop 7
	s_barrier
	s_branch .LBB0_153

.LBB0_192:
	v_mov_b32_e32 v0, v1
	s_mul_hi_i32 s23, s22, 0x2e8ba2e9
	v_mbcnt_lo_u32_b32 v0, -1, v0
	v_mbcnt_hi_u32_b32 v0, -1, v0
	s_lshr_b32 s24, s23, 31
	s_ashr_i32 s23, s23, 3
	v_add_u32_e32 v90, s80, v0
	s_add_i32 s23, s23, s24
	s_mul_i32 s24, s23, 0xb00
	v_lshlrev_b32_e32 v0, 3, v90
	v_ashrrev_i32_e32 v89, 3, v90
	v_and_b32_e32 v88, 56, v0
	v_subrev_u32_e32 v0, s24, v89
	v_add_u32_e32 v0, s20, v0
	v_lshl_or_b32 v0, v0, 10, v88
	v_lshl_add_u64 v[72:73], v[0:1], 1, s[4:5]
	v_lshl_add_u32 v0, s23, 7, v89
	v_lshl_or_b32 v0, v0, 10, v88
	v_lshl_add_u64 v[74:75], v[0:1], 1, s[72:73]
	v_add_co_u32_e32 v76, vcc, s18, v74
	s_waitcnt lgkmcnt(0)
	s_nop 0
	v_addc_co_u32_e32 v77, vcc, 0, v75, vcc
	v_add_co_u32_e32 v78, vcc, s29, v74
	s_nop 0
	s_nop 0
	v_addc_co_u32_e32 v79, vcc, 0, v75, vcc
	v_add_co_u32_e32 v80, vcc, s10, v74
	s_nop 0
	s_nop 0
	v_addc_co_u32_e32 v81, vcc, 0, v75, vcc
	s_nop 0
	s_nop 0
	s_mov_b32 s24, 0x580000
	v_add_co_u32_e32 v82, vcc, s24, v72
	s_mov_b32 s24, 0x590000
	s_nop 0
	v_addc_co_u32_e32 v83, vcc, 0, v73, vcc
	v_add_co_u32_e32 v84, vcc, s18, v72
	s_nop 0
	s_nop 0
	v_addc_co_u32_e32 v85, vcc, 0, v73, vcc
	v_add_co_u32_e32 v86, vcc, s24, v72
	s_nop 0
	s_nop 0
	v_addc_co_u32_e32 v87, vcc, 0, v73, vcc
	s_nop 0
	v_mul_lo_u32 v34, v89, s27
	v_add_lshl_u32 v92, v34, v88, 1
	s_barrier
	v_and_b32_e32 v0, 31, v90
	v_add_u32_e32 v93, 0xd800, v92
	v_ashrrev_i32_e32 v2, 1, v90
	v_and_b32_e32 v91, 0xffffffc0, v2
	v_bfe_u32 v102, v90, 4, 3
	v_lshlrev_b32_e32 v102, 4, v102
	v_xor_b32_e32 v74, v102, v74
	v_xor_b32_e32 v76, v102, v76
	v_xor_b32_e32 v78, v102, v78
	v_xor_b32_e32 v80, v102, v80
	v_xor_b32_e32 v72, v102, v72
	v_xor_b32_e32 v82, v102, v82
	v_xor_b32_e32 v84, v102, v84
	v_xor_b32_e32 v86, v102, v86
	v_bfe_u32 v102, v90, 5, 1
	v_bfe_u32 v103, v90, 1, 3
	v_xor_b32_e32 v102, v102, v103
	v_lshlrev_b32_e32 v102, 4, v102
	v_lshrrev_b32_e32 v103, 1, v90
	v_and_b32_e32 v103, 64, v103
	v_and_b32_e32 v104, 31, v90
	v_or_b32_e32 v103, v103, v104
	v_lshl_or_b32 v94, v103, 7, v102
	v_and_b32_e32 v103, 0x5f, v90
	v_lshl_or_b32 v98, v103, 7, v102
	v_add_u32_e32 v98, 0x4000, v98
	v_xor_b32_e32 v95, 0x20, v94
	v_xor_b32_e32 v99, 0x20, v98
	v_xor_b32_e32 v96, 0x40, v94
	v_xor_b32_e32 v100, 0x40, v98
	v_xor_b32_e32 v97, 0x60, v94
	v_xor_b32_e32 v101, 0x60, v98
	v_mov_b32_e32 v214, 0x80
	v_mov_b32_e32 v215, 0
	s_lshl_b32 vcc_lo, s80, 4
	v_mov_b32_e32 v2, 0
	v_mov_b32_e32 v3, 0
	v_mov_b32_e32 v4, 0
	v_mov_b32_e32 v5, 0
	v_mov_b32_e32 v6, 0
	v_mov_b32_e32 v7, 0
	v_mov_b32_e32 v8, 0
	v_mov_b32_e32 v9, 0
	v_mov_b32_e32 v10, 0
	v_mov_b32_e32 v11, 0
	v_mov_b32_e32 v12, 0
	v_mov_b32_e32 v13, 0
	v_mov_b32_e32 v14, 0
	v_mov_b32_e32 v15, 0
	v_mov_b32_e32 v16, 0
	v_mov_b32_e32 v17, 0
	v_mov_b32_e32 v18, 0
	v_mov_b32_e32 v19, 0
	v_mov_b32_e32 v20, 0
	v_mov_b32_e32 v21, 0
	v_mov_b32_e32 v22, 0
	v_mov_b32_e32 v23, 0
	v_mov_b32_e32 v24, 0
	v_mov_b32_e32 v25, 0
	v_mov_b32_e32 v26, 0
	v_mov_b32_e32 v27, 0
	v_mov_b32_e32 v28, 0
	v_mov_b32_e32 v29, 0
	v_mov_b32_e32 v30, 0
	v_mov_b32_e32 v31, 0
	v_mov_b32_e32 v32, 0
	v_mov_b32_e32 v33, 0
	v_mov_b32_e32 v34, 0
	v_mov_b32_e32 v35, 0
	v_mov_b32_e32 v36, 0
	v_mov_b32_e32 v37, 0
	v_mov_b32_e32 v38, 0
	v_mov_b32_e32 v39, 0
	v_mov_b32_e32 v40, 0
	v_mov_b32_e32 v41, 0
	v_mov_b32_e32 v42, 0
	v_mov_b32_e32 v43, 0
	v_mov_b32_e32 v44, 0
	v_mov_b32_e32 v45, 0
	v_mov_b32_e32 v46, 0
	v_mov_b32_e32 v47, 0
	v_mov_b32_e32 v48, 0
	v_mov_b32_e32 v49, 0
	v_mov_b32_e32 v50, 0
	v_mov_b32_e32 v51, 0
	v_mov_b32_e32 v52, 0
	v_mov_b32_e32 v53, 0
	v_mov_b32_e32 v54, 0
	v_mov_b32_e32 v55, 0
	v_mov_b32_e32 v56, 0
	v_mov_b32_e32 v57, 0
	v_mov_b32_e32 v58, 0
	v_mov_b32_e32 v59, 0
	v_mov_b32_e32 v60, 0
	v_mov_b32_e32 v61, 0
	v_mov_b32_e32 v62, 0
	v_mov_b32_e32 v63, 0
	v_mov_b32_e32 v64, 0
	v_mov_b32_e32 v65, 0
	s_mov_b32 m0, vcc_lo
	s_nop 0
	global_load_lds_dwordx4 v[74:75], off
	s_add_u32 m0, vcc_lo, 0x1000
	s_nop 0
	global_load_lds_dwordx4 v[76:77], off
	s_add_u32 m0, vcc_lo, 0x2000
	s_nop 0
	global_load_lds_dwordx4 v[78:79], off
	s_add_u32 m0, vcc_lo, 0x3000
	s_nop 0
	global_load_lds_dwordx4 v[80:81], off
	s_add_u32 m0, vcc_lo, 0x4000
	s_nop 0
	global_load_lds_dwordx4 v[72:73], off
	s_add_u32 m0, vcc_lo, 0x5000
	s_nop 0
	global_load_lds_dwordx4 v[82:83], off
	s_add_u32 m0, vcc_lo, 0x6000
	s_nop 0
	global_load_lds_dwordx4 v[84:85], off
	s_add_u32 m0, vcc_lo, 0x7000
	s_nop 0
	global_load_lds_dwordx4 v[86:87], off
	v_lshl_add_u64 v[74:75], v[74:75], 0, v[214:215]
	v_lshl_add_u64 v[76:77], v[76:77], 0, v[214:215]
	v_lshl_add_u64 v[78:79], v[78:79], 0, v[214:215]
	v_lshl_add_u64 v[80:81], v[80:81], 0, v[214:215]
	v_lshl_add_u64 v[72:73], v[72:73], 0, v[214:215]
	v_lshl_add_u64 v[82:83], v[82:83], 0, v[214:215]
	v_lshl_add_u64 v[84:85], v[84:85], 0, v[214:215]
	v_lshl_add_u64 v[86:87], v[86:87], 0, v[214:215]
	s_add_u32 m0, vcc_lo, 0x8000
	s_nop 0
	global_load_lds_dwordx4 v[74:75], off
	s_add_u32 m0, vcc_lo, 0x9000
	s_nop 0
	global_load_lds_dwordx4 v[76:77], off
	s_add_u32 m0, vcc_lo, 0xa000
	s_nop 0
	global_load_lds_dwordx4 v[78:79], off
	s_add_u32 m0, vcc_lo, 0xb000
	s_nop 0
	global_load_lds_dwordx4 v[80:81], off
	s_add_u32 m0, vcc_lo, 0xc000
	s_nop 0
	global_load_lds_dwordx4 v[72:73], off
	s_add_u32 m0, vcc_lo, 0xd000
	s_nop 0
	global_load_lds_dwordx4 v[82:83], off
	s_add_u32 m0, vcc_lo, 0xe000
	s_nop 0
	global_load_lds_dwordx4 v[84:85], off
	s_add_u32 m0, vcc_lo, 0xf000
	s_nop 0
	global_load_lds_dwordx4 v[86:87], off
	v_lshl_add_u64 v[74:75], v[74:75], 0, v[214:215]
	v_lshl_add_u64 v[76:77], v[76:77], 0, v[214:215]
	v_lshl_add_u64 v[78:79], v[78:79], 0, v[214:215]
	v_lshl_add_u64 v[80:81], v[80:81], 0, v[214:215]
	v_lshl_add_u64 v[72:73], v[72:73], 0, v[214:215]
	v_lshl_add_u64 v[82:83], v[82:83], 0, v[214:215]
	v_lshl_add_u64 v[84:85], v[84:85], 0, v[214:215]
	v_lshl_add_u64 v[86:87], v[86:87], 0, v[214:215]
	s_mov_b32 vcc_hi, 7
	s_waitcnt vmcnt(8)
	s_barrier
	ds_read_b128 v[166:169], v94
	s_setprio 3
	ds_read_b128 v[170:173], v98
	ds_read_b128 v[174:177], v98 offset:4096
	ds_read_b128 v[178:181], v94 offset:4096
	ds_read_b128 v[182:185], v95
	ds_read_b128 v[188:191], v99
	ds_read_b128 v[192:195], v99 offset:4096
	ds_read_b128 v[206:209], v95 offset:4096
	s_waitcnt lgkmcnt(6)
	v_mfma_f32_32x32x16_bf16 v[34:49], v[166:169], v[170:173], v[34:49]
	ds_read_b128 v[236:239], v96
	s_waitcnt lgkmcnt(5)
	v_mfma_f32_32x32x16_bf16 v[2:17], v[178:181], v[170:173], v[2:17]
	ds_read_b128 v[240:243], v100
	v_mfma_f32_32x32x16_bf16 v[18:33], v[178:181], v[174:177], v[18:33]
	ds_read_b128 v[244:247], v100 offset:4096
	v_mfma_f32_32x32x16_bf16 v[50:65], v[166:169], v[174:177], v[50:65]
	ds_read_b128 v[248:251], v96 offset:4096
	s_waitcnt lgkmcnt(6)
	v_mfma_f32_32x32x16_bf16 v[34:49], v[182:185], v[188:191], v[34:49]
	ds_read_b128 v[126:129], v97
	s_waitcnt lgkmcnt(5)
	v_mfma_f32_32x32x16_bf16 v[2:17], v[206:209], v[188:191], v[2:17]
	ds_read_b128 v[130:133], v101
	v_mfma_f32_32x32x16_bf16 v[18:33], v[206:209], v[192:195], v[18:33]
	ds_read_b128 v[210:213], v101 offset:4096
	v_mfma_f32_32x32x16_bf16 v[50:65], v[182:185], v[192:195], v[50:65]
	ds_read_b128 v[222:225], v97 offset:4096
	s_waitcnt vmcnt(0) lgkmcnt(0)
	s_barrier
.Lg_ffnin_loop:
	v_mfma_f32_32x32x16_bf16 v[34:49], v[236:239], v[240:243], v[34:49]
	s_mov_b32 m0, vcc_lo
	ds_read_b128 v[166:169], v94 offset:32768
	global_load_lds_dwordx4 v[74:75], off
	s_setprio 3
	v_mfma_f32_32x32x16_bf16 v[2:17], v[248:251], v[240:243], v[2:17]
	ds_read_b128 v[170:173], v98 offset:32768
	v_mfma_f32_32x32x16_bf16 v[18:33], v[248:251], v[244:247], v[18:33]
	s_add_u32 m0, vcc_lo, 0x1000
	ds_read_b128 v[174:177], v98 offset:36864
	global_load_lds_dwordx4 v[76:77], off
	v_mfma_f32_32x32x16_bf16 v[50:65], v[236:239], v[244:247], v[50:65]
	ds_read_b128 v[178:181], v94 offset:36864
	v_mfma_f32_32x32x16_bf16 v[34:49], v[126:129], v[130:133], v[34:49]
	s_add_u32 m0, vcc_lo, 0x2000
	ds_read_b128 v[182:185], v95 offset:32768
	global_load_lds_dwordx4 v[78:79], off
	v_mfma_f32_32x32x16_bf16 v[2:17], v[222:225], v[130:133], v[2:17]
	ds_read_b128 v[188:191], v99 offset:32768
	v_mfma_f32_32x32x16_bf16 v[18:33], v[222:225], v[210:213], v[18:33]
	s_add_u32 m0, vcc_lo, 0x3000
	ds_read_b128 v[192:195], v99 offset:36864
	global_load_lds_dwordx4 v[80:81], off
	v_mfma_f32_32x32x16_bf16 v[50:65], v[126:129], v[210:213], v[50:65]
	ds_read_b128 v[206:209], v95 offset:36864
	s_waitcnt lgkmcnt(6)
	v_mfma_f32_32x32x16_bf16 v[34:49], v[166:169], v[170:173], v[34:49]
	s_add_u32 m0, vcc_lo, 0x4000
	ds_read_b128 v[236:239], v96 offset:32768
	global_load_lds_dwordx4 v[72:73], off
	s_waitcnt lgkmcnt(5)
	v_mfma_f32_32x32x16_bf16 v[2:17], v[178:181], v[170:173], v[2:17]
	ds_read_b128 v[240:243], v100 offset:32768
	v_mfma_f32_32x32x16_bf16 v[18:33], v[178:181], v[174:177], v[18:33]
	s_add_u32 m0, vcc_lo, 0x5000
	ds_read_b128 v[244:247], v100 offset:36864
	global_load_lds_dwordx4 v[82:83], off
	v_mfma_f32_32x32x16_bf16 v[50:65], v[166:169], v[174:177], v[50:65]
	ds_read_b128 v[248:251], v96 offset:36864
	s_waitcnt lgkmcnt(6)
	v_mfma_f32_32x32x16_bf16 v[34:49], v[182:185], v[188:191], v[34:49]
	s_add_u32 m0, vcc_lo, 0x6000
	ds_read_b128 v[126:129], v97 offset:32768
	global_load_lds_dwordx4 v[84:85], off
	s_waitcnt lgkmcnt(5)
	v_mfma_f32_32x32x16_bf16 v[2:17], v[206:209], v[188:191], v[2:17]
	ds_read_b128 v[130:133], v101 offset:32768
	v_mfma_f32_32x32x16_bf16 v[18:33], v[206:209], v[192:195], v[18:33]
	s_add_u32 m0, vcc_lo, 0x7000
	ds_read_b128 v[210:213], v101 offset:36864
	global_load_lds_dwordx4 v[86:87], off
	v_mfma_f32_32x32x16_bf16 v[50:65], v[182:185], v[192:195], v[50:65]
	ds_read_b128 v[222:225], v97 offset:36864
	v_lshl_add_u64 v[74:75], v[74:75], 0, v[214:215]
	v_lshl_add_u64 v[76:77], v[76:77], 0, v[214:215]
	v_lshl_add_u64 v[78:79], v[78:79], 0, v[214:215]
	v_lshl_add_u64 v[80:81], v[80:81], 0, v[214:215]
	v_lshl_add_u64 v[72:73], v[72:73], 0, v[214:215]
	v_lshl_add_u64 v[82:83], v[82:83], 0, v[214:215]
	v_lshl_add_u64 v[84:85], v[84:85], 0, v[214:215]
	v_lshl_add_u64 v[86:87], v[86:87], 0, v[214:215]
	s_waitcnt vmcnt(0) lgkmcnt(0)
	s_barrier
	v_mfma_f32_32x32x16_bf16 v[34:49], v[236:239], v[240:243], v[34:49]
	s_add_u32 m0, vcc_lo, 0x8000
	ds_read_b128 v[166:169], v94
	global_load_lds_dwordx4 v[74:75], off
	s_setprio 3
	v_mfma_f32_32x32x16_bf16 v[2:17], v[248:251], v[240:243], v[2:17]
	ds_read_b128 v[170:173], v98
	v_mfma_f32_32x32x16_bf16 v[18:33], v[248:251], v[244:247], v[18:33]
	s_add_u32 m0, vcc_lo, 0x9000
	ds_read_b128 v[174:177], v98 offset:4096
	global_load_lds_dwordx4 v[76:77], off
	v_mfma_f32_32x32x16_bf16 v[50:65], v[236:239], v[244:247], v[50:65]
	ds_read_b128 v[178:181], v94 offset:4096
	v_mfma_f32_32x32x16_bf16 v[34:49], v[126:129], v[130:133], v[34:49]
	s_add_u32 m0, vcc_lo, 0xa000
	ds_read_b128 v[182:185], v95
	global_load_lds_dwordx4 v[78:79], off
	v_mfma_f32_32x32x16_bf16 v[2:17], v[222:225], v[130:133], v[2:17]
	ds_read_b128 v[188:191], v99
	v_mfma_f32_32x32x16_bf16 v[18:33], v[222:225], v[210:213], v[18:33]
	s_add_u32 m0, vcc_lo, 0xb000
	ds_read_b128 v[192:195], v99 offset:4096
	global_load_lds_dwordx4 v[80:81], off
	v_mfma_f32_32x32x16_bf16 v[50:65], v[126:129], v[210:213], v[50:65]
	ds_read_b128 v[206:209], v95 offset:4096
	s_waitcnt lgkmcnt(6)
	v_mfma_f32_32x32x16_bf16 v[34:49], v[166:169], v[170:173], v[34:49]
	s_add_u32 m0, vcc_lo, 0xc000
	ds_read_b128 v[236:239], v96
	global_load_lds_dwordx4 v[72:73], off
	s_waitcnt lgkmcnt(5)
	v_mfma_f32_32x32x16_bf16 v[2:17], v[178:181], v[170:173], v[2:17]
	ds_read_b128 v[240:243], v100
	v_mfma_f32_32x32x16_bf16 v[18:33], v[178:181], v[174:177], v[18:33]
	s_add_u32 m0, vcc_lo, 0xd000
	ds_read_b128 v[244:247], v100 offset:4096
	global_load_lds_dwordx4 v[82:83], off
	v_mfma_f32_32x32x16_bf16 v[50:65], v[166:169], v[174:177], v[50:65]
	ds_read_b128 v[248:251], v96 offset:4096
	s_waitcnt lgkmcnt(6)
	v_mfma_f32_32x32x16_bf16 v[34:49], v[182:185], v[188:191], v[34:49]
	s_add_u32 m0, vcc_lo, 0xe000
	ds_read_b128 v[126:129], v97
	global_load_lds_dwordx4 v[84:85], off
	s_waitcnt lgkmcnt(5)
	v_mfma_f32_32x32x16_bf16 v[2:17], v[206:209], v[188:191], v[2:17]
	ds_read_b128 v[130:133], v101
	v_mfma_f32_32x32x16_bf16 v[18:33], v[206:209], v[192:195], v[18:33]
	s_add_u32 m0, vcc_lo, 0xf000
	ds_read_b128 v[210:213], v101 offset:4096
	global_load_lds_dwordx4 v[86:87], off
	v_mfma_f32_32x32x16_bf16 v[50:65], v[182:185], v[192:195], v[50:65]
	ds_read_b128 v[222:225], v97 offset:4096
	v_lshl_add_u64 v[74:75], v[74:75], 0, v[214:215]
	v_lshl_add_u64 v[76:77], v[76:77], 0, v[214:215]
	v_lshl_add_u64 v[78:79], v[78:79], 0, v[214:215]
	v_lshl_add_u64 v[80:81], v[80:81], 0, v[214:215]
	v_lshl_add_u64 v[72:73], v[72:73], 0, v[214:215]
	v_lshl_add_u64 v[82:83], v[82:83], 0, v[214:215]
	v_lshl_add_u64 v[84:85], v[84:85], 0, v[214:215]
	v_lshl_add_u64 v[86:87], v[86:87], 0, v[214:215]
	s_waitcnt vmcnt(0) lgkmcnt(0)
	s_barrier
	s_sub_u32 vcc_hi, vcc_hi, 1
	s_cmp_lg_u32 vcc_hi, 0
	s_cbranch_scc1 .Lg_ffnin_loop
	v_mfma_f32_32x32x16_bf16 v[34:49], v[236:239], v[240:243], v[34:49]
	ds_read_b128 v[166:169], v94 offset:32768
	s_setprio 3
	v_mfma_f32_32x32x16_bf16 v[2:17], v[248:251], v[240:243], v[2:17]
	ds_read_b128 v[170:173], v98 offset:32768
	v_mfma_f32_32x32x16_bf16 v[18:33], v[248:251], v[244:247], v[18:33]
	ds_read_b128 v[174:177], v98 offset:36864
	v_mfma_f32_32x32x16_bf16 v[50:65], v[236:239], v[244:247], v[50:65]
	ds_read_b128 v[178:181], v94 offset:36864
	v_mfma_f32_32x32x16_bf16 v[34:49], v[126:129], v[130:133], v[34:49]
	ds_read_b128 v[182:185], v95 offset:32768
	v_mfma_f32_32x32x16_bf16 v[2:17], v[222:225], v[130:133], v[2:17]
	ds_read_b128 v[188:191], v99 offset:32768
	v_mfma_f32_32x32x16_bf16 v[18:33], v[222:225], v[210:213], v[18:33]
	ds_read_b128 v[192:195], v99 offset:36864
	v_mfma_f32_32x32x16_bf16 v[50:65], v[126:129], v[210:213], v[50:65]
	ds_read_b128 v[206:209], v95 offset:36864
	s_waitcnt lgkmcnt(6)
	v_mfma_f32_32x32x16_bf16 v[34:49], v[166:169], v[170:173], v[34:49]
	ds_read_b128 v[236:239], v96 offset:32768
	s_waitcnt lgkmcnt(5)
	v_mfma_f32_32x32x16_bf16 v[2:17], v[178:181], v[170:173], v[2:17]
	ds_read_b128 v[240:243], v100 offset:32768
	v_mfma_f32_32x32x16_bf16 v[18:33], v[178:181], v[174:177], v[18:33]
	ds_read_b128 v[244:247], v100 offset:36864
	v_mfma_f32_32x32x16_bf16 v[50:65], v[166:169], v[174:177], v[50:65]
	ds_read_b128 v[248:251], v96 offset:36864
	s_waitcnt lgkmcnt(6)
	v_mfma_f32_32x32x16_bf16 v[34:49], v[182:185], v[188:191], v[34:49]
	ds_read_b128 v[126:129], v97 offset:32768
	s_waitcnt lgkmcnt(5)
	v_mfma_f32_32x32x16_bf16 v[2:17], v[206:209], v[188:191], v[2:17]
	ds_read_b128 v[130:133], v101 offset:32768
	v_mfma_f32_32x32x16_bf16 v[18:33], v[206:209], v[192:195], v[18:33]
	ds_read_b128 v[210:213], v101 offset:36864
	v_mfma_f32_32x32x16_bf16 v[50:65], v[182:185], v[192:195], v[50:65]
	ds_read_b128 v[222:225], v97 offset:36864
	s_waitcnt lgkmcnt(6)
	v_mfma_f32_32x32x16_bf16 v[34:49], v[236:239], v[240:243], v[34:49]
	s_waitcnt lgkmcnt(5)
	v_mfma_f32_32x32x16_bf16 v[50:65], v[236:239], v[244:247], v[50:65]
	s_waitcnt lgkmcnt(4)
	v_mfma_f32_32x32x16_bf16 v[2:17], v[248:251], v[240:243], v[2:17]
	v_mfma_f32_32x32x16_bf16 v[18:33], v[248:251], v[244:247], v[18:33]
	s_waitcnt lgkmcnt(2)
	v_mfma_f32_32x32x16_bf16 v[34:49], v[126:129], v[130:133], v[34:49]
	s_waitcnt lgkmcnt(1)
	v_mfma_f32_32x32x16_bf16 v[50:65], v[126:129], v[210:213], v[50:65]
	s_waitcnt lgkmcnt(0)
	v_mfma_f32_32x32x16_bf16 v[2:17], v[222:225], v[130:133], v[2:17]
	v_mfma_f32_32x32x16_bf16 v[18:33], v[222:225], v[210:213], v[18:33]
	s_nop 7
	s_nop 7
	v_mul_f32_e32 v67, 0xbfb8aa3b, v34
	v_exp_f32_e32 v67, v67
	v_lshrrev_b32_e32 v66, 3, v90
	v_lshlrev_b32_e32 v0, 1, v0
	v_and_or_b32 v66, v66, 4, v91
	v_add_f32_e32 v67, 1.0, v67
	v_rcp_f32_e32 v67, v67
	v_and_or_b32 v0, v90, 64, v0
	s_barrier
	v_mul_f32_e32 v34, v34, v67
	v_mad_u64_u32 v[66:67], s[24:25], v66, s28, v[0:1]
	v_mul_f32_e32 v0, 0xbfb8aa3b, v35
	v_exp_f32_e32 v0, v0
	v_mul_f32_e32 v34, v50, v34
	v_cvt_pk_bf16_f32 v34, v34, s0
	v_add_f32_e32 v0, 1.0, v0
	v_rcp_f32_e32 v0, v0
	ds_write_b16 v66, v34
	s_mul_i32 s23, s23, 0x57500
	s_add_i32 s22, s22, s81
	v_mul_f32_e32 v0, v35, v0
	v_mul_f32_e32 v0, v51, v0
	v_cvt_pk_bf16_f32 v0, v0, s0
	ds_write_b16 v66, v0 offset:144
	v_mul_f32_e32 v0, 0xbfb8aa3b, v36
	v_exp_f32_e32 v0, v0
	s_nop 0
	v_add_f32_e32 v0, 1.0, v0
	v_rcp_f32_e32 v0, v0
	s_nop 0
	v_mul_f32_e32 v0, v36, v0
	v_mul_f32_e32 v0, v52, v0
	v_cvt_pk_bf16_f32 v0, v0, s0
	ds_write_b16 v66, v0 offset:288
	v_mul_f32_e32 v0, 0xbfb8aa3b, v37
	v_exp_f32_e32 v0, v0
	s_nop 0
	v_add_f32_e32 v0, 1.0, v0
	v_rcp_f32_e32 v0, v0
	s_nop 0
	v_mul_f32_e32 v0, v37, v0
	v_mul_f32_e32 v0, v53, v0
	v_cvt_pk_bf16_f32 v0, v0, s0
	ds_write_b16 v66, v0 offset:432
	v_mul_f32_e32 v0, 0xbfb8aa3b, v38
	v_exp_f32_e32 v0, v0
	s_nop 0
	v_add_f32_e32 v0, 1.0, v0
	v_rcp_f32_e32 v0, v0
	s_nop 0
	v_mul_f32_e32 v0, v38, v0
	v_mul_f32_e32 v0, v54, v0
	v_cvt_pk_bf16_f32 v0, v0, s0
	ds_write_b16 v66, v0 offset:1152
	v_mul_f32_e32 v0, 0xbfb8aa3b, v39
	v_exp_f32_e32 v0, v0
	s_nop 0
	v_add_f32_e32 v0, 1.0, v0
	v_rcp_f32_e32 v0, v0
	s_nop 0
	v_mul_f32_e32 v0, v39, v0
	v_mul_f32_e32 v0, v55, v0
	v_cvt_pk_bf16_f32 v0, v0, s0
	ds_write_b16 v66, v0 offset:1296
	v_mul_f32_e32 v0, 0xbfb8aa3b, v40
	v_exp_f32_e32 v0, v0
	s_nop 0
	v_add_f32_e32 v0, 1.0, v0
	v_rcp_f32_e32 v0, v0
	s_nop 0
	v_mul_f32_e32 v0, v40, v0
	v_mul_f32_e32 v0, v56, v0
	v_cvt_pk_bf16_f32 v0, v0, s0
	ds_write_b16 v66, v0 offset:1440
	v_mul_f32_e32 v0, 0xbfb8aa3b, v41
	v_exp_f32_e32 v0, v0
	s_nop 0
	v_add_f32_e32 v0, 1.0, v0
	v_rcp_f32_e32 v0, v0
	s_nop 0
	v_mul_f32_e32 v0, v41, v0
	v_mul_f32_e32 v0, v57, v0
	v_cvt_pk_bf16_f32 v0, v0, s0
	ds_write_b16 v66, v0 offset:1584
	v_mul_f32_e32 v0, 0xbfb8aa3b, v42
	v_exp_f32_e32 v0, v0
	s_nop 0
	v_add_f32_e32 v0, 1.0, v0
	v_rcp_f32_e32 v0, v0
	s_nop 0
	v_mul_f32_e32 v0, v42, v0
	v_mul_f32_e32 v0, v58, v0
	v_cvt_pk_bf16_f32 v0, v0, s0
	ds_write_b16 v66, v0 offset:2304
	v_mul_f32_e32 v0, 0xbfb8aa3b, v43
	v_exp_f32_e32 v0, v0
	s_nop 0
	v_add_f32_e32 v0, 1.0, v0
	v_rcp_f32_e32 v0, v0
	s_nop 0
	v_mul_f32_e32 v0, v43, v0
	v_mul_f32_e32 v0, v59, v0
	v_cvt_pk_bf16_f32 v0, v0, s0
	ds_write_b16 v66, v0 offset:2448
	v_mul_f32_e32 v0, 0xbfb8aa3b, v44
	v_exp_f32_e32 v0, v0
	s_nop 0
	v_add_f32_e32 v0, 1.0, v0
	v_rcp_f32_e32 v0, v0
	s_nop 0
	v_mul_f32_e32 v0, v44, v0
	v_mul_f32_e32 v0, v60, v0
	v_cvt_pk_bf16_f32 v0, v0, s0
	ds_write_b16 v66, v0 offset:2592
	v_mul_f32_e32 v0, 0xbfb8aa3b, v45
	v_exp_f32_e32 v0, v0
	s_nop 0
	v_add_f32_e32 v0, 1.0, v0
	v_rcp_f32_e32 v0, v0
	s_nop 0
	v_mul_f32_e32 v0, v45, v0
	v_mul_f32_e32 v0, v61, v0
	v_cvt_pk_bf16_f32 v0, v0, s0
	ds_write_b16 v66, v0 offset:2736
	v_mul_f32_e32 v0, 0xbfb8aa3b, v46
	v_exp_f32_e32 v0, v0
	s_nop 0
	v_add_f32_e32 v0, 1.0, v0
	v_rcp_f32_e32 v0, v0
	s_nop 0
	v_mul_f32_e32 v0, v46, v0
	v_mul_f32_e32 v0, v62, v0
	v_cvt_pk_bf16_f32 v0, v0, s0
	ds_write_b16 v66, v0 offset:3456
	v_mul_f32_e32 v0, 0xbfb8aa3b, v47
	v_exp_f32_e32 v0, v0
	s_nop 0
	v_add_f32_e32 v0, 1.0, v0
	v_rcp_f32_e32 v0, v0
	s_nop 0
	v_mul_f32_e32 v0, v47, v0
	v_mul_f32_e32 v0, v63, v0
	v_cvt_pk_bf16_f32 v0, v0, s0
	ds_write_b16 v66, v0 offset:3600
	v_mul_f32_e32 v0, 0xbfb8aa3b, v48
	v_exp_f32_e32 v0, v0
	s_nop 0
	v_add_f32_e32 v0, 1.0, v0
	v_rcp_f32_e32 v0, v0
	s_nop 0
	v_mul_f32_e32 v0, v48, v0
	v_mul_f32_e32 v0, v64, v0
	v_cvt_pk_bf16_f32 v0, v0, s0
	ds_write_b16 v66, v0 offset:3744
	v_mul_f32_e32 v0, 0xbfb8aa3b, v49
	v_exp_f32_e32 v0, v0
	s_nop 0
	v_add_f32_e32 v0, 1.0, v0
	v_rcp_f32_e32 v0, v0
	s_nop 0
	v_mul_f32_e32 v0, v49, v0
	v_mul_f32_e32 v0, v65, v0
	v_cvt_pk_bf16_f32 v0, v0, s0
	ds_write_b16 v66, v0 offset:3888
	v_mul_f32_e32 v0, 0xbfb8aa3b, v2
	v_exp_f32_e32 v0, v0
	s_nop 0
	v_add_f32_e32 v0, 1.0, v0
	v_rcp_f32_e32 v0, v0
	s_nop 0
	v_mul_f32_e32 v0, v2, v0
	v_mul_f32_e32 v0, v18, v0
	v_cvt_pk_bf16_f32 v0, v0, s0
	ds_write_b16 v66, v0 offset:4608
	v_mul_f32_e32 v0, 0xbfb8aa3b, v3
	v_exp_f32_e32 v0, v0
	s_nop 0
	v_add_f32_e32 v0, 1.0, v0
	v_rcp_f32_e32 v0, v0
	s_nop 0
	v_mul_f32_e32 v0, v3, v0
	v_mul_f32_e32 v0, v19, v0
	v_cvt_pk_bf16_f32 v0, v0, s0
	ds_write_b16 v66, v0 offset:4752
	v_mul_f32_e32 v0, 0xbfb8aa3b, v4
	v_exp_f32_e32 v0, v0
	s_nop 0
	v_add_f32_e32 v0, 1.0, v0
	v_rcp_f32_e32 v0, v0
	s_nop 0
	v_mul_f32_e32 v0, v4, v0
	v_mul_f32_e32 v0, v20, v0
	v_cvt_pk_bf16_f32 v0, v0, s0
	ds_write_b16 v66, v0 offset:4896
	v_mul_f32_e32 v0, 0xbfb8aa3b, v5
	v_exp_f32_e32 v0, v0
	s_nop 0
	v_add_f32_e32 v0, 1.0, v0
	v_rcp_f32_e32 v0, v0
	s_nop 0
	v_mul_f32_e32 v0, v5, v0
	v_mul_f32_e32 v0, v21, v0
	v_cvt_pk_bf16_f32 v0, v0, s0
	ds_write_b16 v66, v0 offset:5040
	v_mul_f32_e32 v0, 0xbfb8aa3b, v6
	v_exp_f32_e32 v0, v0
	s_nop 0
	v_add_f32_e32 v0, 1.0, v0
	v_rcp_f32_e32 v0, v0
	s_nop 0
	v_mul_f32_e32 v0, v6, v0
	v_mul_f32_e32 v0, v22, v0
	v_cvt_pk_bf16_f32 v0, v0, s0
	ds_write_b16 v66, v0 offset:5760
	v_mul_f32_e32 v0, 0xbfb8aa3b, v7
	v_exp_f32_e32 v0, v0
	s_nop 0
	v_add_f32_e32 v0, 1.0, v0
	v_rcp_f32_e32 v0, v0
	s_nop 0
	v_mul_f32_e32 v0, v7, v0
	v_mul_f32_e32 v0, v23, v0
	v_cvt_pk_bf16_f32 v0, v0, s0
	ds_write_b16 v66, v0 offset:5904
	v_mul_f32_e32 v0, 0xbfb8aa3b, v8
	v_exp_f32_e32 v0, v0
	s_nop 0
	v_add_f32_e32 v0, 1.0, v0
	v_rcp_f32_e32 v0, v0
	s_nop 0
	v_mul_f32_e32 v0, v8, v0
	v_mul_f32_e32 v0, v24, v0
	v_cvt_pk_bf16_f32 v0, v0, s0
	ds_write_b16 v66, v0 offset:6048
	v_mul_f32_e32 v0, 0xbfb8aa3b, v9
	v_exp_f32_e32 v0, v0
	s_nop 0
	v_add_f32_e32 v0, 1.0, v0
	v_rcp_f32_e32 v0, v0
	s_nop 0
	v_mul_f32_e32 v0, v9, v0
	v_mul_f32_e32 v0, v25, v0
	v_cvt_pk_bf16_f32 v0, v0, s0
	ds_write_b16 v66, v0 offset:6192
	v_mul_f32_e32 v0, 0xbfb8aa3b, v10
	v_exp_f32_e32 v0, v0
	s_nop 0
	v_add_f32_e32 v0, 1.0, v0
	v_rcp_f32_e32 v0, v0
	s_nop 0
	v_mul_f32_e32 v0, v10, v0
	v_mul_f32_e32 v0, v26, v0
	v_cvt_pk_bf16_f32 v0, v0, s0
	ds_write_b16 v66, v0 offset:6912
	v_mul_f32_e32 v0, 0xbfb8aa3b, v11
	v_exp_f32_e32 v0, v0
	s_nop 0
	v_add_f32_e32 v0, 1.0, v0
	v_rcp_f32_e32 v0, v0
	s_nop 0
	v_mul_f32_e32 v0, v11, v0
	v_mul_f32_e32 v0, v27, v0
	v_cvt_pk_bf16_f32 v0, v0, s0
	ds_write_b16 v66, v0 offset:7056
	v_mul_f32_e32 v0, 0xbfb8aa3b, v12
	v_exp_f32_e32 v0, v0
	s_nop 0
	v_add_f32_e32 v0, 1.0, v0
	v_rcp_f32_e32 v0, v0
	s_nop 0
	v_mul_f32_e32 v0, v12, v0
	v_mul_f32_e32 v0, v28, v0
	v_cvt_pk_bf16_f32 v0, v0, s0
	ds_write_b16 v66, v0 offset:7200
	v_mul_f32_e32 v0, 0xbfb8aa3b, v13
	v_exp_f32_e32 v0, v0
	s_nop 0
	v_add_f32_e32 v0, 1.0, v0
	v_rcp_f32_e32 v0, v0
	s_nop 0
	v_mul_f32_e32 v0, v13, v0
	v_mul_f32_e32 v0, v29, v0
	v_cvt_pk_bf16_f32 v0, v0, s0
	ds_write_b16 v66, v0 offset:7344
	v_mul_f32_e32 v0, 0xbfb8aa3b, v14
	v_exp_f32_e32 v0, v0
	s_nop 0
	v_add_f32_e32 v0, 1.0, v0
	v_rcp_f32_e32 v0, v0
	s_nop 0
	v_mul_f32_e32 v0, v14, v0
	v_mul_f32_e32 v0, v30, v0
	v_cvt_pk_bf16_f32 v0, v0, s0
	ds_write_b16 v66, v0 offset:8064
	v_mul_f32_e32 v0, 0xbfb8aa3b, v15
	v_exp_f32_e32 v0, v0
	s_nop 0
	v_add_f32_e32 v0, 1.0, v0
	v_rcp_f32_e32 v0, v0
	s_nop 0
	v_mul_f32_e32 v0, v15, v0
	v_mul_f32_e32 v0, v31, v0
	v_cvt_pk_bf16_f32 v0, v0, s0
	ds_write_b16 v66, v0 offset:8208
	v_mul_f32_e32 v0, 0xbfb8aa3b, v16
	v_exp_f32_e32 v0, v0
	s_nop 0
	v_add_f32_e32 v0, 1.0, v0
	v_rcp_f32_e32 v0, v0
	s_nop 0
	v_mul_f32_e32 v0, v16, v0
	v_mul_f32_e32 v0, v32, v0
	v_cvt_pk_bf16_f32 v0, v0, s0
	ds_write_b16 v66, v0 offset:8352
	v_mul_f32_e32 v0, 0xbfb8aa3b, v17
	v_exp_f32_e32 v0, v0
	s_nop 0
	v_add_f32_e32 v0, 1.0, v0
	v_rcp_f32_e32 v0, v0
	s_nop 0
	v_mul_f32_e32 v0, v17, v0
	v_mul_f32_e32 v0, v33, v0
	v_cvt_pk_bf16_f32 v0, v0, s0
	ds_write_b16 v66, v0 offset:8496
	v_mul_lo_u32 v0, v89, s28
	v_lshl_add_u32 v8, v88, 1, v0
	s_waitcnt lgkmcnt(0)
	s_barrier
	ds_read_b128 v[2:5], v8
	v_mul_lo_u32 v0, v89, s26
	v_add_u32_e32 v0, s23, v0
	v_or_b32_e32 v0, v0, v88
	v_add_u32_e32 v0, s20, v0
	v_lshl_add_u64 v[6:7], v[0:1], 1, s[90:91]
	s_waitcnt lgkmcnt(0)
	global_store_dwordx4 v[6:7], v[2:5], off
	ds_read_b128 v[2:5], v8 offset:4608
	v_add_u32_e32 v6, 0x16000, v0
	v_mov_b32_e32 v7, v1
	v_lshl_add_u64 v[6:7], v[6:7], 1, s[90:91]
	s_add_i32 s20, s20, s21
	s_waitcnt lgkmcnt(0)
	global_store_dwordx4 v[6:7], v[2:5], off
	ds_read_b128 v[2:5], v8 offset:9216
	v_add_u32_e32 v6, 0x2c000, v0
	v_mov_b32_e32 v7, v1
	v_lshl_add_u64 v[6:7], v[6:7], 1, s[90:91]
	v_add_u32_e32 v0, 0x42000, v0
	s_waitcnt lgkmcnt(0)
	global_store_dwordx4 v[6:7], v[2:5], off
	ds_read_b128 v[2:5], v8 offset:13824
	v_lshl_add_u64 v[6:7], v[0:1], 1, s[90:91]
	s_cmpk_gt_i32 s22, 0xaff
	s_waitcnt lgkmcnt(0)
	global_store_dwordx4 v[6:7], v[2:5], off
	s_cbranch_scc0 .LBB0_192
	s_movk_i32 s96, 0x48
	s_mov_b32 s19, 0x80000
	s_mov_b32 s14, 0xdb629599
	s_mov_b32 s15, 0xf534ddc0
	s_mov_b32 s16, 0xfc2757d1
	s_mov_b64 s[12:13], s[30:31]
	v_readlane_b32 s22, v255, 2
	v_readlane_b32 s23, v255, 3

.LBB0_206:
	v_mov_b32_e32 v0, v1
	s_and_b32 s34, s25, 0x380
	v_mbcnt_lo_u32_b32 v0, -1, v0
	v_mbcnt_hi_u32_b32 v0, -1, v0
	v_add_u32_e32 v88, s80, v0
	s_and_b32 s31, s24, 0xffffff80
	v_lshlrev_b32_e32 v0, 3, v88
	s_waitcnt lgkmcnt(0)
	v_ashrrev_i32_e32 v2, 3, v88
	v_and_b32_e32 v34, 56, v0
	v_add_u32_e32 v0, s34, v2
	v_lshl_or_b32 v0, v0, 10, v34
	v_lshl_add_u64 v[72:73], v[0:1], 1, s[4:5]
	v_add_u32_e32 v0, s31, v2
	v_lshl_or_b32 v0, v0, 10, v34
	v_lshl_add_u64 v[74:75], v[0:1], 1, s[72:73]
	v_add_co_u32_e32 v76, vcc, s18, v74
	s_mov_b32 s20, 0x20000
	s_nop 0
	v_addc_co_u32_e32 v77, vcc, 0, v75, vcc
	v_add_co_u32_e32 v78, vcc, s20, v74
	v_mul_lo_u32 v35, v2, s96
	s_nop 0
	v_addc_co_u32_e32 v79, vcc, 0, v75, vcc
	v_add_co_u32_e32 v80, vcc, s10, v74
	s_nop 0
	s_nop 0
	v_addc_co_u32_e32 v81, vcc, 0, v75, vcc
	s_nop 0
	s_nop 0
	s_nop 0
	v_add_co_u32_e32 v82, vcc, s18, v72
	v_add_lshl_u32 v90, v35, v34, 1
	s_nop 0
	v_addc_co_u32_e32 v83, vcc, 0, v73, vcc
	v_add_co_u32_e32 v84, vcc, s20, v72
	s_nop 0
	s_nop 0
	v_addc_co_u32_e32 v85, vcc, 0, v73, vcc
	v_add_co_u32_e32 v86, vcc, s10, v72
	s_nop 0
	s_nop 0
	v_addc_co_u32_e32 v87, vcc, 0, v73, vcc
	s_nop 0
	s_barrier
	v_and_b32_e32 v0, 31, v88
	s_movk_i32 s20, 0x90
	v_add_u32_e32 v91, 0xd800, v90
	v_ashrrev_i32_e32 v2, 1, v88
	v_and_b32_e32 v89, 0xffffffc0, v2
	v_bfe_u32 v102, v88, 4, 3
	v_lshlrev_b32_e32 v102, 4, v102
	v_xor_b32_e32 v74, v102, v74
	v_xor_b32_e32 v76, v102, v76
	v_xor_b32_e32 v78, v102, v78
	v_xor_b32_e32 v80, v102, v80
	v_xor_b32_e32 v72, v102, v72
	v_xor_b32_e32 v82, v102, v82
	v_xor_b32_e32 v84, v102, v84
	v_xor_b32_e32 v86, v102, v86
	v_bfe_u32 v102, v88, 5, 1
	v_bfe_u32 v103, v88, 1, 3
	v_xor_b32_e32 v102, v102, v103
	v_lshlrev_b32_e32 v102, 4, v102
	v_lshrrev_b32_e32 v103, 1, v88
	v_and_b32_e32 v103, 64, v103
	v_and_b32_e32 v104, 31, v88
	v_or_b32_e32 v103, v103, v104
	v_lshl_or_b32 v94, v103, 7, v102
	v_and_b32_e32 v103, 0x5f, v88
	v_lshl_or_b32 v98, v103, 7, v102
	v_add_u32_e32 v98, 0x4000, v98
	v_xor_b32_e32 v95, 0x20, v94
	v_xor_b32_e32 v99, 0x20, v98
	v_xor_b32_e32 v96, 0x40, v94
	v_xor_b32_e32 v100, 0x40, v98
	v_xor_b32_e32 v97, 0x60, v94
	v_xor_b32_e32 v101, 0x60, v98
	v_mov_b32_e32 v214, 0x80
	v_mov_b32_e32 v215, 0
	s_lshl_b32 vcc_lo, s80, 4
	v_mov_b32_e32 v2, 0
	v_mov_b32_e32 v3, 0
	v_mov_b32_e32 v4, 0
	v_mov_b32_e32 v5, 0
	v_mov_b32_e32 v6, 0
	v_mov_b32_e32 v7, 0
	v_mov_b32_e32 v8, 0
	v_mov_b32_e32 v9, 0
	v_mov_b32_e32 v10, 0
	v_mov_b32_e32 v11, 0
	v_mov_b32_e32 v12, 0
	v_mov_b32_e32 v13, 0
	v_mov_b32_e32 v14, 0
	v_mov_b32_e32 v15, 0
	v_mov_b32_e32 v16, 0
	v_mov_b32_e32 v17, 0
	v_mov_b32_e32 v18, 0
	v_mov_b32_e32 v19, 0
	v_mov_b32_e32 v20, 0
	v_mov_b32_e32 v21, 0
	v_mov_b32_e32 v22, 0
	v_mov_b32_e32 v23, 0
	v_mov_b32_e32 v24, 0
	v_mov_b32_e32 v25, 0
	v_mov_b32_e32 v26, 0
	v_mov_b32_e32 v27, 0
	v_mov_b32_e32 v28, 0
	v_mov_b32_e32 v29, 0
	v_mov_b32_e32 v30, 0
	v_mov_b32_e32 v31, 0
	v_mov_b32_e32 v32, 0
	v_mov_b32_e32 v33, 0
	v_mov_b32_e32 v34, 0
	v_mov_b32_e32 v35, 0
	v_mov_b32_e32 v36, 0
	v_mov_b32_e32 v37, 0
	v_mov_b32_e32 v38, 0
	v_mov_b32_e32 v39, 0
	v_mov_b32_e32 v40, 0
	v_mov_b32_e32 v41, 0
	v_mov_b32_e32 v42, 0
	v_mov_b32_e32 v43, 0
	v_mov_b32_e32 v44, 0
	v_mov_b32_e32 v45, 0
	v_mov_b32_e32 v46, 0
	v_mov_b32_e32 v47, 0
	v_mov_b32_e32 v48, 0
	v_mov_b32_e32 v49, 0
	v_mov_b32_e32 v50, 0
	v_mov_b32_e32 v51, 0
	v_mov_b32_e32 v52, 0
	v_mov_b32_e32 v53, 0
	v_mov_b32_e32 v54, 0
	v_mov_b32_e32 v55, 0
	v_mov_b32_e32 v56, 0
	v_mov_b32_e32 v57, 0
	v_mov_b32_e32 v58, 0
	v_mov_b32_e32 v59, 0
	v_mov_b32_e32 v60, 0
	v_mov_b32_e32 v61, 0
	v_mov_b32_e32 v62, 0
	v_mov_b32_e32 v63, 0
	v_mov_b32_e32 v64, 0
	v_mov_b32_e32 v65, 0
	s_mov_b32 m0, vcc_lo
	s_nop 0
	global_load_lds_dwordx4 v[74:75], off
	s_add_u32 m0, vcc_lo, 0x1000
	s_nop 0
	global_load_lds_dwordx4 v[76:77], off
	s_add_u32 m0, vcc_lo, 0x2000
	s_nop 0
	global_load_lds_dwordx4 v[78:79], off
	s_add_u32 m0, vcc_lo, 0x3000
	s_nop 0
	global_load_lds_dwordx4 v[80:81], off
	s_add_u32 m0, vcc_lo, 0x4000
	s_nop 0
	global_load_lds_dwordx4 v[72:73], off
	s_add_u32 m0, vcc_lo, 0x5000
	s_nop 0
	global_load_lds_dwordx4 v[82:83], off
	s_add_u32 m0, vcc_lo, 0x6000
	s_nop 0
	global_load_lds_dwordx4 v[84:85], off
	s_add_u32 m0, vcc_lo, 0x7000
	s_nop 0
	global_load_lds_dwordx4 v[86:87], off
	v_lshl_add_u64 v[74:75], v[74:75], 0, v[214:215]
	v_lshl_add_u64 v[76:77], v[76:77], 0, v[214:215]
	v_lshl_add_u64 v[78:79], v[78:79], 0, v[214:215]
	v_lshl_add_u64 v[80:81], v[80:81], 0, v[214:215]
	v_lshl_add_u64 v[72:73], v[72:73], 0, v[214:215]
	v_lshl_add_u64 v[82:83], v[82:83], 0, v[214:215]
	v_lshl_add_u64 v[84:85], v[84:85], 0, v[214:215]
	v_lshl_add_u64 v[86:87], v[86:87], 0, v[214:215]
	s_add_u32 m0, vcc_lo, 0x8000
	s_nop 0
	global_load_lds_dwordx4 v[74:75], off
	s_add_u32 m0, vcc_lo, 0x9000
	s_nop 0
	global_load_lds_dwordx4 v[76:77], off
	s_add_u32 m0, vcc_lo, 0xa000
	s_nop 0
	global_load_lds_dwordx4 v[78:79], off
	s_add_u32 m0, vcc_lo, 0xb000
	s_nop 0
	global_load_lds_dwordx4 v[80:81], off
	s_add_u32 m0, vcc_lo, 0xc000
	s_nop 0
	global_load_lds_dwordx4 v[72:73], off
	s_add_u32 m0, vcc_lo, 0xd000
	s_nop 0
	global_load_lds_dwordx4 v[82:83], off
	s_add_u32 m0, vcc_lo, 0xe000
	s_nop 0
	global_load_lds_dwordx4 v[84:85], off
	s_add_u32 m0, vcc_lo, 0xf000
	s_nop 0
	global_load_lds_dwordx4 v[86:87], off
	v_lshl_add_u64 v[74:75], v[74:75], 0, v[214:215]
	v_lshl_add_u64 v[76:77], v[76:77], 0, v[214:215]
	v_lshl_add_u64 v[78:79], v[78:79], 0, v[214:215]
	v_lshl_add_u64 v[80:81], v[80:81], 0, v[214:215]
	v_lshl_add_u64 v[72:73], v[72:73], 0, v[214:215]
	v_lshl_add_u64 v[82:83], v[82:83], 0, v[214:215]
	v_lshl_add_u64 v[84:85], v[84:85], 0, v[214:215]
	v_lshl_add_u64 v[86:87], v[86:87], 0, v[214:215]
	s_mov_b32 vcc_hi, 7
	s_waitcnt vmcnt(8)
	s_barrier
	ds_read_b128 v[166:169], v94
	s_setprio 3
	ds_read_b128 v[170:173], v98
	ds_read_b128 v[174:177], v98 offset:4096
	ds_read_b128 v[178:181], v94 offset:4096
	ds_read_b128 v[182:185], v95
	ds_read_b128 v[188:191], v99
	ds_read_b128 v[192:195], v99 offset:4096
	ds_read_b128 v[206:209], v95 offset:4096
	s_waitcnt lgkmcnt(6)
	v_mfma_f32_32x32x16_bf16 v[34:49], v[166:169], v[170:173], v[34:49]
	ds_read_b128 v[236:239], v96
	s_waitcnt lgkmcnt(5)
	v_mfma_f32_32x32x16_bf16 v[2:17], v[178:181], v[170:173], v[2:17]
	ds_read_b128 v[240:243], v100
	v_mfma_f32_32x32x16_bf16 v[18:33], v[178:181], v[174:177], v[18:33]
	ds_read_b128 v[244:247], v100 offset:4096
	v_mfma_f32_32x32x16_bf16 v[50:65], v[166:169], v[174:177], v[50:65]
	ds_read_b128 v[248:251], v96 offset:4096
	s_waitcnt lgkmcnt(6)
	v_mfma_f32_32x32x16_bf16 v[34:49], v[182:185], v[188:191], v[34:49]
	ds_read_b128 v[126:129], v97
	s_waitcnt lgkmcnt(5)
	v_mfma_f32_32x32x16_bf16 v[2:17], v[206:209], v[188:191], v[2:17]
	ds_read_b128 v[130:133], v101
	v_mfma_f32_32x32x16_bf16 v[18:33], v[206:209], v[192:195], v[18:33]
	ds_read_b128 v[210:213], v101 offset:4096
	v_mfma_f32_32x32x16_bf16 v[50:65], v[182:185], v[192:195], v[50:65]
	ds_read_b128 v[222:225], v97 offset:4096
	s_waitcnt vmcnt(0) lgkmcnt(0)
	s_barrier
.Lg_resid0_loop:
	v_mfma_f32_32x32x16_bf16 v[34:49], v[236:239], v[240:243], v[34:49]
	s_mov_b32 m0, vcc_lo
	ds_read_b128 v[166:169], v94 offset:32768
	global_load_lds_dwordx4 v[74:75], off
	s_setprio 3
	v_mfma_f32_32x32x16_bf16 v[2:17], v[248:251], v[240:243], v[2:17]
	ds_read_b128 v[170:173], v98 offset:32768
	v_mfma_f32_32x32x16_bf16 v[18:33], v[248:251], v[244:247], v[18:33]
	s_add_u32 m0, vcc_lo, 0x1000
	ds_read_b128 v[174:177], v98 offset:36864
	global_load_lds_dwordx4 v[76:77], off
	v_mfma_f32_32x32x16_bf16 v[50:65], v[236:239], v[244:247], v[50:65]
	ds_read_b128 v[178:181], v94 offset:36864
	v_mfma_f32_32x32x16_bf16 v[34:49], v[126:129], v[130:133], v[34:49]
	s_add_u32 m0, vcc_lo, 0x2000
	ds_read_b128 v[182:185], v95 offset:32768
	global_load_lds_dwordx4 v[78:79], off
	v_mfma_f32_32x32x16_bf16 v[2:17], v[222:225], v[130:133], v[2:17]
	ds_read_b128 v[188:191], v99 offset:32768
	v_mfma_f32_32x32x16_bf16 v[18:33], v[222:225], v[210:213], v[18:33]
	s_add_u32 m0, vcc_lo, 0x3000
	ds_read_b128 v[192:195], v99 offset:36864
	global_load_lds_dwordx4 v[80:81], off
	v_mfma_f32_32x32x16_bf16 v[50:65], v[126:129], v[210:213], v[50:65]
	ds_read_b128 v[206:209], v95 offset:36864
	s_waitcnt lgkmcnt(6)
	v_mfma_f32_32x32x16_bf16 v[34:49], v[166:169], v[170:173], v[34:49]
	s_add_u32 m0, vcc_lo, 0x4000
	ds_read_b128 v[236:239], v96 offset:32768
	global_load_lds_dwordx4 v[72:73], off
	s_waitcnt lgkmcnt(5)
	v_mfma_f32_32x32x16_bf16 v[2:17], v[178:181], v[170:173], v[2:17]
	ds_read_b128 v[240:243], v100 offset:32768
	v_mfma_f32_32x32x16_bf16 v[18:33], v[178:181], v[174:177], v[18:33]
	s_add_u32 m0, vcc_lo, 0x5000
	ds_read_b128 v[244:247], v100 offset:36864
	global_load_lds_dwordx4 v[82:83], off
	v_mfma_f32_32x32x16_bf16 v[50:65], v[166:169], v[174:177], v[50:65]
	ds_read_b128 v[248:251], v96 offset:36864
	s_waitcnt lgkmcnt(6)
	v_mfma_f32_32x32x16_bf16 v[34:49], v[182:185], v[188:191], v[34:49]
	s_add_u32 m0, vcc_lo, 0x6000
	ds_read_b128 v[126:129], v97 offset:32768
	global_load_lds_dwordx4 v[84:85], off
	s_waitcnt lgkmcnt(5)
	v_mfma_f32_32x32x16_bf16 v[2:17], v[206:209], v[188:191], v[2:17]
	ds_read_b128 v[130:133], v101 offset:32768
	v_mfma_f32_32x32x16_bf16 v[18:33], v[206:209], v[192:195], v[18:33]
	s_add_u32 m0, vcc_lo, 0x7000
	ds_read_b128 v[210:213], v101 offset:36864
	global_load_lds_dwordx4 v[86:87], off
	v_mfma_f32_32x32x16_bf16 v[50:65], v[182:185], v[192:195], v[50:65]
	ds_read_b128 v[222:225], v97 offset:36864
	v_lshl_add_u64 v[74:75], v[74:75], 0, v[214:215]
	v_lshl_add_u64 v[76:77], v[76:77], 0, v[214:215]
	v_lshl_add_u64 v[78:79], v[78:79], 0, v[214:215]
	v_lshl_add_u64 v[80:81], v[80:81], 0, v[214:215]
	v_lshl_add_u64 v[72:73], v[72:73], 0, v[214:215]
	v_lshl_add_u64 v[82:83], v[82:83], 0, v[214:215]
	v_lshl_add_u64 v[84:85], v[84:85], 0, v[214:215]
	v_lshl_add_u64 v[86:87], v[86:87], 0, v[214:215]
	s_waitcnt vmcnt(0) lgkmcnt(0)
	s_barrier
	v_mfma_f32_32x32x16_bf16 v[34:49], v[236:239], v[240:243], v[34:49]
	s_add_u32 m0, vcc_lo, 0x8000
	ds_read_b128 v[166:169], v94
	global_load_lds_dwordx4 v[74:75], off
	s_setprio 3
	v_mfma_f32_32x32x16_bf16 v[2:17], v[248:251], v[240:243], v[2:17]
	ds_read_b128 v[170:173], v98
	v_mfma_f32_32x32x16_bf16 v[18:33], v[248:251], v[244:247], v[18:33]
	s_add_u32 m0, vcc_lo, 0x9000
	ds_read_b128 v[174:177], v98 offset:4096
	global_load_lds_dwordx4 v[76:77], off
	v_mfma_f32_32x32x16_bf16 v[50:65], v[236:239], v[244:247], v[50:65]
	ds_read_b128 v[178:181], v94 offset:4096
	v_mfma_f32_32x32x16_bf16 v[34:49], v[126:129], v[130:133], v[34:49]
	s_add_u32 m0, vcc_lo, 0xa000
	ds_read_b128 v[182:185], v95
	global_load_lds_dwordx4 v[78:79], off
	v_mfma_f32_32x32x16_bf16 v[2:17], v[222:225], v[130:133], v[2:17]
	ds_read_b128 v[188:191], v99
	v_mfma_f32_32x32x16_bf16 v[18:33], v[222:225], v[210:213], v[18:33]
	s_add_u32 m0, vcc_lo, 0xb000
	ds_read_b128 v[192:195], v99 offset:4096
	global_load_lds_dwordx4 v[80:81], off
	v_mfma_f32_32x32x16_bf16 v[50:65], v[126:129], v[210:213], v[50:65]
	ds_read_b128 v[206:209], v95 offset:4096
	s_waitcnt lgkmcnt(6)
	v_mfma_f32_32x32x16_bf16 v[34:49], v[166:169], v[170:173], v[34:49]
	s_add_u32 m0, vcc_lo, 0xc000
	ds_read_b128 v[236:239], v96
	global_load_lds_dwordx4 v[72:73], off
	s_waitcnt lgkmcnt(5)
	v_mfma_f32_32x32x16_bf16 v[2:17], v[178:181], v[170:173], v[2:17]
	ds_read_b128 v[240:243], v100
	v_mfma_f32_32x32x16_bf16 v[18:33], v[178:181], v[174:177], v[18:33]
	s_add_u32 m0, vcc_lo, 0xd000
	ds_read_b128 v[244:247], v100 offset:4096
	global_load_lds_dwordx4 v[82:83], off
	v_mfma_f32_32x32x16_bf16 v[50:65], v[166:169], v[174:177], v[50:65]
	ds_read_b128 v[248:251], v96 offset:4096
	s_waitcnt lgkmcnt(6)
	v_mfma_f32_32x32x16_bf16 v[34:49], v[182:185], v[188:191], v[34:49]
	s_add_u32 m0, vcc_lo, 0xe000
	ds_read_b128 v[126:129], v97
	global_load_lds_dwordx4 v[84:85], off
	s_waitcnt lgkmcnt(5)
	v_mfma_f32_32x32x16_bf16 v[2:17], v[206:209], v[188:191], v[2:17]
	ds_read_b128 v[130:133], v101
	v_mfma_f32_32x32x16_bf16 v[18:33], v[206:209], v[192:195], v[18:33]
	s_add_u32 m0, vcc_lo, 0xf000
	ds_read_b128 v[210:213], v101 offset:4096
	global_load_lds_dwordx4 v[86:87], off
	v_mfma_f32_32x32x16_bf16 v[50:65], v[182:185], v[192:195], v[50:65]
	ds_read_b128 v[222:225], v97 offset:4096
	v_lshl_add_u64 v[74:75], v[74:75], 0, v[214:215]
	v_lshl_add_u64 v[76:77], v[76:77], 0, v[214:215]
	v_lshl_add_u64 v[78:79], v[78:79], 0, v[214:215]
	v_lshl_add_u64 v[80:81], v[80:81], 0, v[214:215]
	v_lshl_add_u64 v[72:73], v[72:73], 0, v[214:215]
	v_lshl_add_u64 v[82:83], v[82:83], 0, v[214:215]
	v_lshl_add_u64 v[84:85], v[84:85], 0, v[214:215]
	v_lshl_add_u64 v[86:87], v[86:87], 0, v[214:215]
	s_waitcnt vmcnt(0) lgkmcnt(0)
	s_barrier
	s_sub_u32 vcc_hi, vcc_hi, 1
	s_cmp_lg_u32 vcc_hi, 0
	s_cbranch_scc1 .Lg_resid0_loop
	v_mfma_f32_32x32x16_bf16 v[34:49], v[236:239], v[240:243], v[34:49]
	ds_read_b128 v[166:169], v94 offset:32768
	s_setprio 3
	v_mfma_f32_32x32x16_bf16 v[2:17], v[248:251], v[240:243], v[2:17]
	ds_read_b128 v[170:173], v98 offset:32768
	v_mfma_f32_32x32x16_bf16 v[18:33], v[248:251], v[244:247], v[18:33]
	ds_read_b128 v[174:177], v98 offset:36864
	v_mfma_f32_32x32x16_bf16 v[50:65], v[236:239], v[244:247], v[50:65]
	ds_read_b128 v[178:181], v94 offset:36864
	v_mfma_f32_32x32x16_bf16 v[34:49], v[126:129], v[130:133], v[34:49]
	ds_read_b128 v[182:185], v95 offset:32768
	v_mfma_f32_32x32x16_bf16 v[2:17], v[222:225], v[130:133], v[2:17]
	ds_read_b128 v[188:191], v99 offset:32768
	v_mfma_f32_32x32x16_bf16 v[18:33], v[222:225], v[210:213], v[18:33]
	ds_read_b128 v[192:195], v99 offset:36864
	v_mfma_f32_32x32x16_bf16 v[50:65], v[126:129], v[210:213], v[50:65]
	ds_read_b128 v[206:209], v95 offset:36864
	s_waitcnt lgkmcnt(6)
	v_mfma_f32_32x32x16_bf16 v[34:49], v[166:169], v[170:173], v[34:49]
	ds_read_b128 v[236:239], v96 offset:32768
	s_waitcnt lgkmcnt(5)
	v_mfma_f32_32x32x16_bf16 v[2:17], v[178:181], v[170:173], v[2:17]
	ds_read_b128 v[240:243], v100 offset:32768
	v_mfma_f32_32x32x16_bf16 v[18:33], v[178:181], v[174:177], v[18:33]
	ds_read_b128 v[244:247], v100 offset:36864
	v_mfma_f32_32x32x16_bf16 v[50:65], v[166:169], v[174:177], v[50:65]
	ds_read_b128 v[248:251], v96 offset:36864
	s_waitcnt lgkmcnt(6)
	v_mfma_f32_32x32x16_bf16 v[34:49], v[182:185], v[188:191], v[34:49]
	ds_read_b128 v[126:129], v97 offset:32768
	s_waitcnt lgkmcnt(5)
	v_mfma_f32_32x32x16_bf16 v[2:17], v[206:209], v[188:191], v[2:17]
	ds_read_b128 v[130:133], v101 offset:32768
	v_mfma_f32_32x32x16_bf16 v[18:33], v[206:209], v[192:195], v[18:33]
	ds_read_b128 v[210:213], v101 offset:36864
	v_mfma_f32_32x32x16_bf16 v[50:65], v[182:185], v[192:195], v[50:65]
	ds_read_b128 v[222:225], v97 offset:36864
	s_waitcnt lgkmcnt(6)
	v_mfma_f32_32x32x16_bf16 v[34:49], v[236:239], v[240:243], v[34:49]
	s_waitcnt lgkmcnt(5)
	v_mfma_f32_32x32x16_bf16 v[50:65], v[236:239], v[244:247], v[50:65]
	s_waitcnt lgkmcnt(4)
	v_mfma_f32_32x32x16_bf16 v[2:17], v[248:251], v[240:243], v[2:17]
	v_mfma_f32_32x32x16_bf16 v[18:33], v[248:251], v[244:247], v[18:33]
	s_waitcnt lgkmcnt(2)
	v_mfma_f32_32x32x16_bf16 v[34:49], v[126:129], v[130:133], v[34:49]
	s_waitcnt lgkmcnt(1)
	v_mfma_f32_32x32x16_bf16 v[50:65], v[126:129], v[210:213], v[50:65]
	s_waitcnt lgkmcnt(0)
	v_mfma_f32_32x32x16_bf16 v[2:17], v[222:225], v[130:133], v[2:17]
	v_mfma_f32_32x32x16_bf16 v[18:33], v[222:225], v[210:213], v[18:33]
	s_nop 7
	s_nop 7
	s_andn2_b64 vcc, exec, s[22:23]
	s_mov_b64 s[20:21], s[26:27]
	s_barrier
	s_cbranch_vccnz .LBB0_205
	s_load_dwordx2 s[20:21], s[28:29], 0x0
	s_branch .LBB0_205

.LBB0_513:
	v_mov_b32_e32 v0, v1
	s_and_b32 s28, s25, 0x1f80
	v_mbcnt_lo_u32_b32 v0, -1, v0
	v_mbcnt_hi_u32_b32 v0, -1, v0
	v_add_u32_e32 v88, s80, v0
	s_and_b32 s27, s24, 0xffffff80
	s_waitcnt lgkmcnt(0)
	v_ashrrev_i32_e32 v2, 3, v88
	v_lshlrev_b32_e32 v89, 3, v88
	v_and_b32_e32 v34, 56, v89
	v_add_u32_e32 v0, s28, v2
	v_lshl_or_b32 v0, v0, 10, v34
	v_lshl_add_u64 v[72:73], v[0:1], 1, s[4:5]
	v_add_u32_e32 v0, s27, v2
	v_lshl_or_b32 v0, v0, 10, v34
	v_lshl_add_u64 v[74:75], v[0:1], 1, s[72:73]
	v_add_co_u32_e32 v76, vcc, s18, v74
	s_mov_b32 s20, 0x20000
	s_nop 0
	v_addc_co_u32_e32 v77, vcc, 0, v75, vcc
	v_add_co_u32_e32 v78, vcc, s20, v74
	v_mul_lo_u32 v35, v2, s31
	s_nop 0
	v_addc_co_u32_e32 v79, vcc, 0, v75, vcc
	v_add_co_u32_e32 v80, vcc, s10, v74
	s_nop 0
	s_nop 0
	v_addc_co_u32_e32 v81, vcc, 0, v75, vcc
	s_nop 0
	s_nop 0
	s_nop 0
	v_add_co_u32_e32 v82, vcc, s18, v72
	v_add_lshl_u32 v91, v35, v34, 1
	s_nop 0
	v_addc_co_u32_e32 v83, vcc, 0, v73, vcc
	v_add_co_u32_e32 v84, vcc, s20, v72
	s_nop 0
	s_nop 0
	v_addc_co_u32_e32 v85, vcc, 0, v73, vcc
	v_add_co_u32_e32 v86, vcc, s10, v72
	s_nop 0
	s_nop 0
	v_addc_co_u32_e32 v87, vcc, 0, v73, vcc
	s_nop 0
	s_waitcnt lgkmcnt(0)
	s_barrier
	v_and_b32_e32 v0, 31, v88
	s_movk_i32 s20, 0x90
	v_add_u32_e32 v92, 0xd800, v91
	v_ashrrev_i32_e32 v2, 1, v88
	v_and_b32_e32 v90, 0xffffffc0, v2
	v_bfe_u32 v102, v88, 4, 3
	v_lshlrev_b32_e32 v102, 4, v102
	v_xor_b32_e32 v74, v102, v74
	v_xor_b32_e32 v76, v102, v76
	v_xor_b32_e32 v78, v102, v78
	v_xor_b32_e32 v80, v102, v80
	v_xor_b32_e32 v72, v102, v72
	v_xor_b32_e32 v82, v102, v82
	v_xor_b32_e32 v84, v102, v84
	v_xor_b32_e32 v86, v102, v86
	v_bfe_u32 v102, v88, 5, 1
	v_bfe_u32 v103, v88, 1, 3
	v_xor_b32_e32 v102, v102, v103
	v_lshlrev_b32_e32 v102, 4, v102
	v_lshrrev_b32_e32 v103, 1, v88
	v_and_b32_e32 v103, 64, v103
	v_and_b32_e32 v104, 31, v88
	v_or_b32_e32 v103, v103, v104
	v_lshl_or_b32 v94, v103, 7, v102
	v_and_b32_e32 v103, 0x5f, v88
	v_lshl_or_b32 v98, v103, 7, v102
	v_add_u32_e32 v98, 0x4000, v98
	v_xor_b32_e32 v95, 0x20, v94
	v_xor_b32_e32 v99, 0x20, v98
	v_xor_b32_e32 v96, 0x40, v94
	v_xor_b32_e32 v100, 0x40, v98
	v_xor_b32_e32 v97, 0x60, v94
	v_xor_b32_e32 v101, 0x60, v98
	v_mov_b32_e32 v214, 0x80
	v_mov_b32_e32 v215, 0
	s_lshl_b32 vcc_lo, s80, 4
	v_mov_b32_e32 v2, 0
	v_mov_b32_e32 v3, 0
	v_mov_b32_e32 v4, 0
	v_mov_b32_e32 v5, 0
	v_mov_b32_e32 v6, 0
	v_mov_b32_e32 v7, 0
	v_mov_b32_e32 v8, 0
	v_mov_b32_e32 v9, 0
	v_mov_b32_e32 v10, 0
	v_mov_b32_e32 v11, 0
	v_mov_b32_e32 v12, 0
	v_mov_b32_e32 v13, 0
	v_mov_b32_e32 v14, 0
	v_mov_b32_e32 v15, 0
	v_mov_b32_e32 v16, 0
	v_mov_b32_e32 v17, 0
	v_mov_b32_e32 v18, 0
	v_mov_b32_e32 v19, 0
	v_mov_b32_e32 v20, 0
	v_mov_b32_e32 v21, 0
	v_mov_b32_e32 v22, 0
	v_mov_b32_e32 v23, 0
	v_mov_b32_e32 v24, 0
	v_mov_b32_e32 v25, 0
	v_mov_b32_e32 v26, 0
	v_mov_b32_e32 v27, 0
	v_mov_b32_e32 v28, 0
	v_mov_b32_e32 v29, 0
	v_mov_b32_e32 v30, 0
	v_mov_b32_e32 v31, 0
	v_mov_b32_e32 v32, 0
	v_mov_b32_e32 v33, 0
	v_mov_b32_e32 v34, 0
	v_mov_b32_e32 v35, 0
	v_mov_b32_e32 v36, 0
	v_mov_b32_e32 v37, 0
	v_mov_b32_e32 v38, 0
	v_mov_b32_e32 v39, 0
	v_mov_b32_e32 v40, 0
	v_mov_b32_e32 v41, 0
	v_mov_b32_e32 v42, 0
	v_mov_b32_e32 v43, 0
	v_mov_b32_e32 v44, 0
	v_mov_b32_e32 v45, 0
	v_mov_b32_e32 v46, 0
	v_mov_b32_e32 v47, 0
	v_mov_b32_e32 v48, 0
	v_mov_b32_e32 v49, 0
	v_mov_b32_e32 v50, 0
	v_mov_b32_e32 v51, 0
	v_mov_b32_e32 v52, 0
	v_mov_b32_e32 v53, 0
	v_mov_b32_e32 v54, 0
	v_mov_b32_e32 v55, 0
	v_mov_b32_e32 v56, 0
	v_mov_b32_e32 v57, 0
	v_mov_b32_e32 v58, 0
	v_mov_b32_e32 v59, 0
	v_mov_b32_e32 v60, 0
	v_mov_b32_e32 v61, 0
	v_mov_b32_e32 v62, 0
	v_mov_b32_e32 v63, 0
	v_mov_b32_e32 v64, 0
	v_mov_b32_e32 v65, 0
	s_mov_b32 m0, vcc_lo
	s_nop 0
	global_load_lds_dwordx4 v[74:75], off
	s_add_u32 m0, vcc_lo, 0x1000
	s_nop 0
	global_load_lds_dwordx4 v[76:77], off
	s_add_u32 m0, vcc_lo, 0x2000
	s_nop 0
	global_load_lds_dwordx4 v[78:79], off
	s_add_u32 m0, vcc_lo, 0x3000
	s_nop 0
	global_load_lds_dwordx4 v[80:81], off
	s_add_u32 m0, vcc_lo, 0x4000
	s_nop 0
	global_load_lds_dwordx4 v[72:73], off
	s_add_u32 m0, vcc_lo, 0x5000
	s_nop 0
	global_load_lds_dwordx4 v[82:83], off
	s_add_u32 m0, vcc_lo, 0x6000
	s_nop 0
	global_load_lds_dwordx4 v[84:85], off
	s_add_u32 m0, vcc_lo, 0x7000
	s_nop 0
	global_load_lds_dwordx4 v[86:87], off
	v_lshl_add_u64 v[74:75], v[74:75], 0, v[214:215]
	v_lshl_add_u64 v[76:77], v[76:77], 0, v[214:215]
	v_lshl_add_u64 v[78:79], v[78:79], 0, v[214:215]
	v_lshl_add_u64 v[80:81], v[80:81], 0, v[214:215]
	v_lshl_add_u64 v[72:73], v[72:73], 0, v[214:215]
	v_lshl_add_u64 v[82:83], v[82:83], 0, v[214:215]
	v_lshl_add_u64 v[84:85], v[84:85], 0, v[214:215]
	v_lshl_add_u64 v[86:87], v[86:87], 0, v[214:215]
	s_add_u32 m0, vcc_lo, 0x8000
	s_nop 0
	global_load_lds_dwordx4 v[74:75], off
	s_add_u32 m0, vcc_lo, 0x9000
	s_nop 0
	global_load_lds_dwordx4 v[76:77], off
	s_add_u32 m0, vcc_lo, 0xa000
	s_nop 0
	global_load_lds_dwordx4 v[78:79], off
	s_add_u32 m0, vcc_lo, 0xb000
	s_nop 0
	global_load_lds_dwordx4 v[80:81], off
	s_add_u32 m0, vcc_lo, 0xc000
	s_nop 0
	global_load_lds_dwordx4 v[72:73], off
	s_add_u32 m0, vcc_lo, 0xd000
	s_nop 0
	global_load_lds_dwordx4 v[82:83], off
	s_add_u32 m0, vcc_lo, 0xe000
	s_nop 0
	global_load_lds_dwordx4 v[84:85], off
	s_add_u32 m0, vcc_lo, 0xf000
	s_nop 0
	global_load_lds_dwordx4 v[86:87], off
	v_lshl_add_u64 v[74:75], v[74:75], 0, v[214:215]
	v_lshl_add_u64 v[76:77], v[76:77], 0, v[214:215]
	v_lshl_add_u64 v[78:79], v[78:79], 0, v[214:215]
	v_lshl_add_u64 v[80:81], v[80:81], 0, v[214:215]
	v_lshl_add_u64 v[72:73], v[72:73], 0, v[214:215]
	v_lshl_add_u64 v[82:83], v[82:83], 0, v[214:215]
	v_lshl_add_u64 v[84:85], v[84:85], 0, v[214:215]
	v_lshl_add_u64 v[86:87], v[86:87], 0, v[214:215]
	s_mov_b32 vcc_hi, 7
	s_waitcnt vmcnt(8)
	s_barrier
	ds_read_b128 v[166:169], v94
	s_setprio 3
	ds_read_b128 v[170:173], v98
	ds_read_b128 v[174:177], v98 offset:4096
	ds_read_b128 v[178:181], v94 offset:4096
	ds_read_b128 v[182:185], v95
	ds_read_b128 v[188:191], v99
	ds_read_b128 v[192:195], v99 offset:4096
	ds_read_b128 v[206:209], v95 offset:4096
	s_waitcnt lgkmcnt(6)
	v_mfma_f32_32x32x16_bf16 v[50:65], v[166:169], v[170:173], v[50:65]
	ds_read_b128 v[236:239], v96
	s_waitcnt lgkmcnt(5)
	v_mfma_f32_32x32x16_bf16 v[18:33], v[178:181], v[170:173], v[18:33]
	ds_read_b128 v[240:243], v100
	v_mfma_f32_32x32x16_bf16 v[2:17], v[178:181], v[174:177], v[2:17]
	ds_read_b128 v[244:247], v100 offset:4096
	v_mfma_f32_32x32x16_bf16 v[34:49], v[166:169], v[174:177], v[34:49]
	ds_read_b128 v[248:251], v96 offset:4096
	s_waitcnt lgkmcnt(6)
	v_mfma_f32_32x32x16_bf16 v[50:65], v[182:185], v[188:191], v[50:65]
	ds_read_b128 v[126:129], v97
	s_waitcnt lgkmcnt(5)
	v_mfma_f32_32x32x16_bf16 v[18:33], v[206:209], v[188:191], v[18:33]
	ds_read_b128 v[130:133], v101
	v_mfma_f32_32x32x16_bf16 v[2:17], v[206:209], v[192:195], v[2:17]
	ds_read_b128 v[210:213], v101 offset:4096
	v_mfma_f32_32x32x16_bf16 v[34:49], v[182:185], v[192:195], v[34:49]
	ds_read_b128 v[222:225], v97 offset:4096
	s_waitcnt vmcnt(0) lgkmcnt(0)
	s_barrier
.Lg_gemm1_loop:
	v_mfma_f32_32x32x16_bf16 v[50:65], v[236:239], v[240:243], v[50:65]
	s_mov_b32 m0, vcc_lo
	ds_read_b128 v[166:169], v94 offset:32768
	global_load_lds_dwordx4 v[74:75], off
	s_setprio 3
	v_mfma_f32_32x32x16_bf16 v[18:33], v[248:251], v[240:243], v[18:33]
	ds_read_b128 v[170:173], v98 offset:32768
	v_mfma_f32_32x32x16_bf16 v[2:17], v[248:251], v[244:247], v[2:17]
	s_add_u32 m0, vcc_lo, 0x1000
	ds_read_b128 v[174:177], v98 offset:36864
	global_load_lds_dwordx4 v[76:77], off
	v_mfma_f32_32x32x16_bf16 v[34:49], v[236:239], v[244:247], v[34:49]
	ds_read_b128 v[178:181], v94 offset:36864
	v_mfma_f32_32x32x16_bf16 v[50:65], v[126:129], v[130:133], v[50:65]
	s_add_u32 m0, vcc_lo, 0x2000
	ds_read_b128 v[182:185], v95 offset:32768
	global_load_lds_dwordx4 v[78:79], off
	v_mfma_f32_32x32x16_bf16 v[18:33], v[222:225], v[130:133], v[18:33]
	ds_read_b128 v[188:191], v99 offset:32768
	v_mfma_f32_32x32x16_bf16 v[2:17], v[222:225], v[210:213], v[2:17]
	s_add_u32 m0, vcc_lo, 0x3000
	ds_read_b128 v[192:195], v99 offset:36864
	global_load_lds_dwordx4 v[80:81], off
	v_mfma_f32_32x32x16_bf16 v[34:49], v[126:129], v[210:213], v[34:49]
	ds_read_b128 v[206:209], v95 offset:36864
	s_waitcnt lgkmcnt(6)
	v_mfma_f32_32x32x16_bf16 v[50:65], v[166:169], v[170:173], v[50:65]
	s_add_u32 m0, vcc_lo, 0x4000
	ds_read_b128 v[236:239], v96 offset:32768
	global_load_lds_dwordx4 v[72:73], off
	s_waitcnt lgkmcnt(5)
	v_mfma_f32_32x32x16_bf16 v[18:33], v[178:181], v[170:173], v[18:33]
	ds_read_b128 v[240:243], v100 offset:32768
	v_mfma_f32_32x32x16_bf16 v[2:17], v[178:181], v[174:177], v[2:17]
	s_add_u32 m0, vcc_lo, 0x5000
	ds_read_b128 v[244:247], v100 offset:36864
	global_load_lds_dwordx4 v[82:83], off
	v_mfma_f32_32x32x16_bf16 v[34:49], v[166:169], v[174:177], v[34:49]
	ds_read_b128 v[248:251], v96 offset:36864
	s_waitcnt lgkmcnt(6)
	v_mfma_f32_32x32x16_bf16 v[50:65], v[182:185], v[188:191], v[50:65]
	s_add_u32 m0, vcc_lo, 0x6000
	ds_read_b128 v[126:129], v97 offset:32768
	global_load_lds_dwordx4 v[84:85], off
	s_waitcnt lgkmcnt(5)
	v_mfma_f32_32x32x16_bf16 v[18:33], v[206:209], v[188:191], v[18:33]
	ds_read_b128 v[130:133], v101 offset:32768
	v_mfma_f32_32x32x16_bf16 v[2:17], v[206:209], v[192:195], v[2:17]
	s_add_u32 m0, vcc_lo, 0x7000
	ds_read_b128 v[210:213], v101 offset:36864
	global_load_lds_dwordx4 v[86:87], off
	v_mfma_f32_32x32x16_bf16 v[34:49], v[182:185], v[192:195], v[34:49]
	ds_read_b128 v[222:225], v97 offset:36864
	v_lshl_add_u64 v[74:75], v[74:75], 0, v[214:215]
	v_lshl_add_u64 v[76:77], v[76:77], 0, v[214:215]
	v_lshl_add_u64 v[78:79], v[78:79], 0, v[214:215]
	v_lshl_add_u64 v[80:81], v[80:81], 0, v[214:215]
	v_lshl_add_u64 v[72:73], v[72:73], 0, v[214:215]
	v_lshl_add_u64 v[82:83], v[82:83], 0, v[214:215]
	v_lshl_add_u64 v[84:85], v[84:85], 0, v[214:215]
	v_lshl_add_u64 v[86:87], v[86:87], 0, v[214:215]
	s_waitcnt vmcnt(0) lgkmcnt(0)
	s_barrier
	v_mfma_f32_32x32x16_bf16 v[50:65], v[236:239], v[240:243], v[50:65]
	s_add_u32 m0, vcc_lo, 0x8000
	ds_read_b128 v[166:169], v94
	global_load_lds_dwordx4 v[74:75], off
	s_setprio 3
	v_mfma_f32_32x32x16_bf16 v[18:33], v[248:251], v[240:243], v[18:33]
	ds_read_b128 v[170:173], v98
	v_mfma_f32_32x32x16_bf16 v[2:17], v[248:251], v[244:247], v[2:17]
	s_add_u32 m0, vcc_lo, 0x9000
	ds_read_b128 v[174:177], v98 offset:4096
	global_load_lds_dwordx4 v[76:77], off
	v_mfma_f32_32x32x16_bf16 v[34:49], v[236:239], v[244:247], v[34:49]
	ds_read_b128 v[178:181], v94 offset:4096
	v_mfma_f32_32x32x16_bf16 v[50:65], v[126:129], v[130:133], v[50:65]
	s_add_u32 m0, vcc_lo, 0xa000
	ds_read_b128 v[182:185], v95
	global_load_lds_dwordx4 v[78:79], off
	v_mfma_f32_32x32x16_bf16 v[18:33], v[222:225], v[130:133], v[18:33]
	ds_read_b128 v[188:191], v99
	v_mfma_f32_32x32x16_bf16 v[2:17], v[222:225], v[210:213], v[2:17]
	s_add_u32 m0, vcc_lo, 0xb000
	ds_read_b128 v[192:195], v99 offset:4096
	global_load_lds_dwordx4 v[80:81], off
	v_mfma_f32_32x32x16_bf16 v[34:49], v[126:129], v[210:213], v[34:49]
	ds_read_b128 v[206:209], v95 offset:4096
	s_waitcnt lgkmcnt(6)
	v_mfma_f32_32x32x16_bf16 v[50:65], v[166:169], v[170:173], v[50:65]
	s_add_u32 m0, vcc_lo, 0xc000
	ds_read_b128 v[236:239], v96
	global_load_lds_dwordx4 v[72:73], off
	s_waitcnt lgkmcnt(5)
	v_mfma_f32_32x32x16_bf16 v[18:33], v[178:181], v[170:173], v[18:33]
	ds_read_b128 v[240:243], v100
	v_mfma_f32_32x32x16_bf16 v[2:17], v[178:181], v[174:177], v[2:17]
	s_add_u32 m0, vcc_lo, 0xd000
	ds_read_b128 v[244:247], v100 offset:4096
	global_load_lds_dwordx4 v[82:83], off
	v_mfma_f32_32x32x16_bf16 v[34:49], v[166:169], v[174:177], v[34:49]
	ds_read_b128 v[248:251], v96 offset:4096
	s_waitcnt lgkmcnt(6)
	v_mfma_f32_32x32x16_bf16 v[50:65], v[182:185], v[188:191], v[50:65]
	s_add_u32 m0, vcc_lo, 0xe000
	ds_read_b128 v[126:129], v97
	global_load_lds_dwordx4 v[84:85], off
	s_waitcnt lgkmcnt(5)
	v_mfma_f32_32x32x16_bf16 v[18:33], v[206:209], v[188:191], v[18:33]
	ds_read_b128 v[130:133], v101
	v_mfma_f32_32x32x16_bf16 v[2:17], v[206:209], v[192:195], v[2:17]
	s_add_u32 m0, vcc_lo, 0xf000
	ds_read_b128 v[210:213], v101 offset:4096
	global_load_lds_dwordx4 v[86:87], off
	v_mfma_f32_32x32x16_bf16 v[34:49], v[182:185], v[192:195], v[34:49]
	ds_read_b128 v[222:225], v97 offset:4096
	v_lshl_add_u64 v[74:75], v[74:75], 0, v[214:215]
	v_lshl_add_u64 v[76:77], v[76:77], 0, v[214:215]
	v_lshl_add_u64 v[78:79], v[78:79], 0, v[214:215]
	v_lshl_add_u64 v[80:81], v[80:81], 0, v[214:215]
	v_lshl_add_u64 v[72:73], v[72:73], 0, v[214:215]
	v_lshl_add_u64 v[82:83], v[82:83], 0, v[214:215]
	v_lshl_add_u64 v[84:85], v[84:85], 0, v[214:215]
	v_lshl_add_u64 v[86:87], v[86:87], 0, v[214:215]
	s_waitcnt vmcnt(0) lgkmcnt(0)
	s_barrier
	s_sub_u32 vcc_hi, vcc_hi, 1
	s_cmp_lg_u32 vcc_hi, 0
	s_cbranch_scc1 .Lg_gemm1_loop
	v_mfma_f32_32x32x16_bf16 v[50:65], v[236:239], v[240:243], v[50:65]
	ds_read_b128 v[166:169], v94 offset:32768
	s_setprio 3
	v_mfma_f32_32x32x16_bf16 v[18:33], v[248:251], v[240:243], v[18:33]
	ds_read_b128 v[170:173], v98 offset:32768
	v_mfma_f32_32x32x16_bf16 v[2:17], v[248:251], v[244:247], v[2:17]
	ds_read_b128 v[174:177], v98 offset:36864
	v_mfma_f32_32x32x16_bf16 v[34:49], v[236:239], v[244:247], v[34:49]
	ds_read_b128 v[178:181], v94 offset:36864
	v_mfma_f32_32x32x16_bf16 v[50:65], v[126:129], v[130:133], v[50:65]
	ds_read_b128 v[182:185], v95 offset:32768
	v_mfma_f32_32x32x16_bf16 v[18:33], v[222:225], v[130:133], v[18:33]
	ds_read_b128 v[188:191], v99 offset:32768
	v_mfma_f32_32x32x16_bf16 v[2:17], v[222:225], v[210:213], v[2:17]
	ds_read_b128 v[192:195], v99 offset:36864
	v_mfma_f32_32x32x16_bf16 v[34:49], v[126:129], v[210:213], v[34:49]
	ds_read_b128 v[206:209], v95 offset:36864
	s_waitcnt lgkmcnt(6)
	v_mfma_f32_32x32x16_bf16 v[50:65], v[166:169], v[170:173], v[50:65]
	ds_read_b128 v[236:239], v96 offset:32768
	s_waitcnt lgkmcnt(5)
	v_mfma_f32_32x32x16_bf16 v[18:33], v[178:181], v[170:173], v[18:33]
	ds_read_b128 v[240:243], v100 offset:32768
	v_mfma_f32_32x32x16_bf16 v[2:17], v[178:181], v[174:177], v[2:17]
	ds_read_b128 v[244:247], v100 offset:36864
	v_mfma_f32_32x32x16_bf16 v[34:49], v[166:169], v[174:177], v[34:49]
	ds_read_b128 v[248:251], v96 offset:36864
	s_waitcnt lgkmcnt(6)
	v_mfma_f32_32x32x16_bf16 v[50:65], v[182:185], v[188:191], v[50:65]
	ds_read_b128 v[126:129], v97 offset:32768
	s_waitcnt lgkmcnt(5)
	v_mfma_f32_32x32x16_bf16 v[18:33], v[206:209], v[188:191], v[18:33]
	ds_read_b128 v[130:133], v101 offset:32768
	v_mfma_f32_32x32x16_bf16 v[2:17], v[206:209], v[192:195], v[2:17]
	ds_read_b128 v[210:213], v101 offset:36864
	v_mfma_f32_32x32x16_bf16 v[34:49], v[182:185], v[192:195], v[34:49]
	ds_read_b128 v[222:225], v97 offset:36864
	s_waitcnt lgkmcnt(6)
	v_mfma_f32_32x32x16_bf16 v[50:65], v[236:239], v[240:243], v[50:65]
	s_waitcnt lgkmcnt(5)
	v_mfma_f32_32x32x16_bf16 v[34:49], v[236:239], v[244:247], v[34:49]
	s_waitcnt lgkmcnt(4)
	v_mfma_f32_32x32x16_bf16 v[18:33], v[248:251], v[240:243], v[18:33]
	v_mfma_f32_32x32x16_bf16 v[2:17], v[248:251], v[244:247], v[2:17]
	s_waitcnt lgkmcnt(2)
	v_mfma_f32_32x32x16_bf16 v[50:65], v[126:129], v[130:133], v[50:65]
	s_waitcnt lgkmcnt(1)
	v_mfma_f32_32x32x16_bf16 v[34:49], v[126:129], v[210:213], v[34:49]
	s_waitcnt lgkmcnt(0)
	v_mfma_f32_32x32x16_bf16 v[18:33], v[222:225], v[130:133], v[18:33]
	v_mfma_f32_32x32x16_bf16 v[2:17], v[222:225], v[210:213], v[2:17]
	s_nop 7
	s_nop 7
	s_cmpk_lt_u32 s28, 0x400
	s_movk_i32 s29, 0x400
	s_barrier
	s_cbranch_scc1 .LBB0_522
	s_cmpk_gt_u32 s28, 0xdff
	s_mov_b64 s[22:23], -1
	s_cbranch_scc0 .LBB0_520
	s_cmpk_gt_u32 s28, 0x13ff
	s_mov_b64 s[20:21], -1
	s_cbranch_scc0 .LBB0_517
	s_add_i32 s30, s28, 0xffffec00
	s_mov_b64 s[20:21], 0
